# merge K-loops chained across segments (next segment's first tile prefetched during sigmoid/accumulate); outproj phase rewritten on the DMA K-loop with gate-fused packed stores
# speedup vs baseline: 1.1598x; 1.0156x over previous
; #define G_STORE(S, bf) { *(uint4*)&s->a[bf][srow][skc] = S##a0; *(uint4*)&s->a[bf][srow + 32][skc] = S##a1; \
;     if (MB == 2) { *(uint4*)&s->a[bf][srow + 64][skc] = S##a2; *(uint4*)&s->a[bf][srow + 96][skc] = S##a3; } \
;     *(uint4*)&s->b[bf][srow][skc] = S##b0; *(uint4*)&s->b[bf][srow + 32][skc] = S##b1; *(uint4*)&s->b[bf][srow + 64][skc] = S##b2; *(uint4*)&s->b[bf][srow + 96][skc] = S##b3; }
; template <int MB, bool PF2 = true>
; DI void gemm_main(const u16* __restrict__ A, int lda, const u16* __restrict__ B, int ldb, int K, f32x16 (&acc)[MB][2], GemmLds* s, int tid) {
;     ...
;   for (int kt = 0; kt < KT; kt += 2) {
;     { const int k2 = min((kt + 2) * 64, klast); G_LOAD(q, k2); }
;     __builtin_amdgcn_sched_barrier(0);
;     G_COMPUTE(0);
;     G_STORE(p, 1);
;     __syncthreads();
;     { const int k3 = min((kt + 3) * 64, klast); G_LOAD(p, k3); }
;     __builtin_amdgcn_sched_barrier(0);
;     G_COMPUTE(1);
;     G_STORE(q, 0);
;     __syncthreads();
;   }
.Lip_last:
	ds_read_b128 v[94:97], v71 offset:32768
	ds_read_b128 v[102:105], v75 offset:32768
	ds_read_b128 v[98:101], v71 offset:36864
	ds_read_b128 v[106:109], v75 offset:36864
	s_waitcnt lgkmcnt(4)
	v_mfma_f32_32x32x16_bf16 v[50:65], v[78:81], v[86:89], v[50:65]
	v_mfma_f32_32x32x16_bf16 v[18:33], v[78:81], v[90:93], v[18:33]
	v_mfma_f32_32x32x16_bf16 v[34:49], v[82:85], v[86:89], v[34:49]
	v_mfma_f32_32x32x16_bf16 v[2:17], v[82:85], v[90:93], v[2:17]
	ds_read_b128 v[78:81], v72 offset:32768
	ds_read_b128 v[86:89], v76 offset:32768
	ds_read_b128 v[82:85], v72 offset:36864
	ds_read_b128 v[90:93], v76 offset:36864
	s_waitcnt lgkmcnt(4)
	v_mfma_f32_32x32x16_bf16 v[50:65], v[94:97], v[102:105], v[50:65]
	v_mfma_f32_32x32x16_bf16 v[18:33], v[94:97], v[106:109], v[18:33]
	v_mfma_f32_32x32x16_bf16 v[34:49], v[98:101], v[102:105], v[34:49]
	v_mfma_f32_32x32x16_bf16 v[2:17], v[98:101], v[106:109], v[2:17]
	ds_read_b128 v[94:97], v73 offset:32768
	ds_read_b128 v[102:105], v77 offset:32768
	ds_read_b128 v[98:101], v73 offset:36864
	ds_read_b128 v[106:109], v77 offset:36864
	s_waitcnt lgkmcnt(4)
	v_mfma_f32_32x32x16_bf16 v[50:65], v[78:81], v[86:89], v[50:65]
	v_mfma_f32_32x32x16_bf16 v[18:33], v[78:81], v[90:93], v[18:33]
	v_mfma_f32_32x32x16_bf16 v[34:49], v[82:85], v[86:89], v[34:49]
	v_mfma_f32_32x32x16_bf16 v[2:17], v[82:85], v[90:93], v[2:17]
	s_waitcnt vmcnt(0) lgkmcnt(0)
	s_barrier
	v_mfma_f32_32x32x16_bf16 v[50:65], v[94:97], v[102:105], v[50:65]
	v_mfma_f32_32x32x16_bf16 v[18:33], v[94:97], v[106:109], v[18:33]
	v_mfma_f32_32x32x16_bf16 v[34:49], v[98:101], v[102:105], v[34:49]
	v_mfma_f32_32x32x16_bf16 v[2:17], v[98:101], v[106:109], v[2:17]
	s_nop 7
	s_nop 7

; #define G_STORE(S, bf) { *(uint4*)&s->a[bf][srow][skc] = S##a0; *(uint4*)&s->a[bf][srow + 32][skc] = S##a1; \
;     if (MB == 2) { *(uint4*)&s->a[bf][srow + 64][skc] = S##a2; *(uint4*)&s->a[bf][srow + 96][skc] = S##a3; } \
;     *(uint4*)&s->b[bf][srow][skc] = S##b0; *(uint4*)&s->b[bf][srow + 32][skc] = S##b1; *(uint4*)&s->b[bf][srow + 64][skc] = S##b2; *(uint4*)&s->b[bf][srow + 96][skc] = S##b3; }
; template <int MB, bool PF2 = true>
; DI void gemm_main(const u16* __restrict__ A, int lda, const u16* __restrict__ B, int ldb, int K, f32x16 (&acc)[MB][2], GemmLds* s, int tid) {
;     ...
;   const int klast = K - 64;
;   G_LOAD(p, 64);
;   __syncthreads();
;   for (int kt = 0; kt < KT; kt += 2) {
;     { const int k2 = min((kt + 2) * 64, klast); G_LOAD(q, k2); }
;     __builtin_amdgcn_sched_barrier(0);
;     G_COMPUTE(0);
;     G_STORE(p, 1);
;     __syncthreads();
;     { const int k3 = min((kt + 3) * 64, klast); G_LOAD(p, k3); }
;     __builtin_amdgcn_sched_barrier(0);
;     G_COMPUTE(1);
;     G_STORE(q, 0);
;     __syncthreads();
;   }
; DI void phase_merge(const Params& p, int l, char* smem, int tid) {
;     ...
;   for (int it = (dyn ? fetch_item(qc, smem) : (int)blockIdx.x); it < 544 * 8; it = (dyn ? fetch_item(qc, smem) : it + (int)gridDim.x)) {
;     const int mt = it >> 3, nt = it & 7, m0 = mt * 64, n0 = nt * 128;
;     if (l == 1 && (mt % 68) < 4) continue;
;     f32x16 accT[1][2]; zero_acc<1>(accT);
; #pragma unroll 1
;     for (int i = 0; i < 4; i++) {
;       if ((ZERO_MASK >> i) & 1) continue;
;       unsigned sg[2][8];
;       {
;         f32x16 m[1][2]; zero_acc<1>(m);
;         gemm_main<1>(p.xn + (size_t)m0 * 1024, 1024, p.WtM + (size_t)l * 4096 * 1024 + ((size_t)i * 1024 + n0) * 1024, 1024, 1024, m, s, tid);
.Lmg_decoded:
	s_lshr_b32 s3, s19, 14
	s_lshl_b32 s2, s19, 18
	s_add_u32 s2, s96, s2
	s_addc_u32 s3, s97, s3
	s_lshl_b32 s19, s13, 18
	v_mov_b32_e32 v2, 0
	v_mov_b32_e32 v3, 0
	v_mov_b32_e32 v4, 0
	v_mov_b32_e32 v5, 0
	v_mov_b32_e32 v6, 0
	v_mov_b32_e32 v7, 0
	v_mov_b32_e32 v8, 0
	v_mov_b32_e32 v9, 0
	v_mov_b32_e32 v10, 0
	v_mov_b32_e32 v11, 0
	v_mov_b32_e32 v12, 0
	v_mov_b32_e32 v13, 0
	v_mov_b32_e32 v14, 0
	v_mov_b32_e32 v15, 0
	v_mov_b32_e32 v16, 0
	v_mov_b32_e32 v17, 0
	v_mov_b32_e32 v18, 0
	v_mov_b32_e32 v19, 0
	v_mov_b32_e32 v20, 0
	v_mov_b32_e32 v21, 0
	v_mov_b32_e32 v22, 0
	v_mov_b32_e32 v23, 0
	v_mov_b32_e32 v24, 0
	v_mov_b32_e32 v25, 0
	v_mov_b32_e32 v26, 0
	v_mov_b32_e32 v27, 0
	v_mov_b32_e32 v28, 0
	v_mov_b32_e32 v29, 0
	v_mov_b32_e32 v30, 0
	v_mov_b32_e32 v31, 0
	v_mov_b32_e32 v32, 0
	v_mov_b32_e32 v33, 0
	v_mov_b32_e32 v34, 0
	v_mov_b32_e32 v35, 0
	v_mov_b32_e32 v36, 0
	v_mov_b32_e32 v37, 0
	v_mov_b32_e32 v38, 0
	v_mov_b32_e32 v39, 0
	v_mov_b32_e32 v40, 0
	v_mov_b32_e32 v41, 0
	v_mov_b32_e32 v42, 0
	v_mov_b32_e32 v43, 0
	v_mov_b32_e32 v44, 0
	v_mov_b32_e32 v45, 0
	v_mov_b32_e32 v46, 0
	v_mov_b32_e32 v47, 0
	v_mov_b32_e32 v48, 0
	v_mov_b32_e32 v49, 0
	v_mov_b32_e32 v50, 0
	v_mov_b32_e32 v51, 0
	v_mov_b32_e32 v52, 0
	v_mov_b32_e32 v53, 0
	v_mov_b32_e32 v54, 0
	v_mov_b32_e32 v55, 0
	v_mov_b32_e32 v56, 0
	v_mov_b32_e32 v57, 0
	v_mov_b32_e32 v58, 0
	v_mov_b32_e32 v59, 0
	v_mov_b32_e32 v60, 0
	v_mov_b32_e32 v61, 0
	v_mov_b32_e32 v62, 0
	v_mov_b32_e32 v63, 0
	v_mov_b32_e32 v64, 0
	v_mov_b32_e32 v65, 0
	s_mov_b32 s13, 0
	s_mov_b32 s4, s2
	s_mov_b32 s5, s3
	s_add_u32 s8, s14, s19
	s_addc_u32 s9, s15, 0
	s_add_u32 m0, s10, 0x0
	s_nop 0
	global_load_lds_dwordx4 v200, s[4:5]
	s_add_u32 m0, s10, 0x400
	s_nop 0
	global_load_lds_dwordx4 v201, s[4:5]
	s_add_u32 m0, s10, 0x800
	s_nop 0
	global_load_lds_dwordx4 v202, s[4:5]
	s_add_u32 m0, s10, 0xc00
	s_nop 0
	global_load_lds_dwordx4 v203, s[4:5]
	s_add_u32 m0, s10, 0x4000
	s_nop 0
	global_load_lds_dwordx4 v200, s[8:9]
	s_add_u32 m0, s10, 0x4400
	s_nop 0
	global_load_lds_dwordx4 v201, s[8:9]
	s_add_u32 m0, s10, 0x4800
	s_nop 0
	global_load_lds_dwordx4 v202, s[8:9]
	s_add_u32 m0, s10, 0x4c00
	s_nop 0
	global_load_lds_dwordx4 v203, s[8:9]
	s_add_u32 s4, s4, 128
	s_addc_u32 s5, s5, 0
	s_add_u32 s8, s8, 128
	s_addc_u32 s9, s9, 0
.Lmg_seg:
	v_mov_b32_e32 v66, 0
	v_mov_b32_e32 v67, 0
	v_mov_b32_e32 v68, 0
	v_mov_b32_e32 v69, 0
	v_mov_b32_e32 v70, 0
	v_mov_b32_e32 v71, 0
	v_mov_b32_e32 v72, 0
	v_mov_b32_e32 v73, 0
	v_mov_b32_e32 v74, 0
	v_mov_b32_e32 v75, 0
	v_mov_b32_e32 v76, 0
	v_mov_b32_e32 v77, 0
	v_mov_b32_e32 v78, 0
	v_mov_b32_e32 v79, 0
	v_mov_b32_e32 v80, 0
	v_mov_b32_e32 v81, 0
	v_mov_b32_e32 v82, 0
	v_mov_b32_e32 v83, 0
	v_mov_b32_e32 v84, 0
	v_mov_b32_e32 v85, 0
	v_mov_b32_e32 v86, 0
	v_mov_b32_e32 v87, 0
	v_mov_b32_e32 v88, 0
	v_mov_b32_e32 v89, 0
	v_mov_b32_e32 v90, 0
	v_mov_b32_e32 v91, 0
	v_mov_b32_e32 v92, 0
	v_mov_b32_e32 v93, 0
	v_mov_b32_e32 v94, 0
	v_mov_b32_e32 v95, 0
	v_mov_b32_e32 v96, 0
	v_mov_b32_e32 v97, 0
	v_mov_b32_e32 v98, 0
	v_mov_b32_e32 v99, 0
	v_mov_b32_e32 v100, 0
	v_mov_b32_e32 v101, 0
	v_mov_b32_e32 v102, 0
	v_mov_b32_e32 v103, 0
	v_mov_b32_e32 v104, 0
	v_mov_b32_e32 v105, 0
	v_mov_b32_e32 v106, 0
	v_mov_b32_e32 v107, 0
	v_mov_b32_e32 v108, 0
	v_mov_b32_e32 v109, 0
	v_mov_b32_e32 v110, 0
	v_mov_b32_e32 v111, 0
	v_mov_b32_e32 v112, 0
	v_mov_b32_e32 v113, 0
	v_mov_b32_e32 v114, 0
	v_mov_b32_e32 v115, 0
	v_mov_b32_e32 v116, 0
	v_mov_b32_e32 v117, 0
	v_mov_b32_e32 v118, 0
	v_mov_b32_e32 v119, 0
	v_mov_b32_e32 v120, 0
	v_mov_b32_e32 v121, 0
	v_mov_b32_e32 v122, 0
	v_mov_b32_e32 v123, 0
	v_mov_b32_e32 v124, 0
	v_mov_b32_e32 v125, 0
	v_mov_b32_e32 v126, 0
	v_mov_b32_e32 v127, 0
	v_mov_b32_e32 v128, 0
	v_mov_b32_e32 v129, 0
	s_waitcnt vmcnt(0) lgkmcnt(0)
	s_barrier
	ds_read_b128 v[224:227], v138 offset:0
	ds_read_b128 v[232:235], v142 offset:0
	ds_read_b128 v[228:231], v138 offset:4096
	ds_read_b128 v[236:239], v142 offset:4096
	s_mov_b32 s11, 7
.Lmgm_loop:
	s_add_u32 m0, s10, 0x8000
	ds_read_b128 v[240:243], v139 offset:0
	global_load_lds_dwordx4 v200, s[4:5]
	s_add_u32 m0, s10, 0x8400
	ds_read_b128 v[192:195], v143 offset:0
	global_load_lds_dwordx4 v201, s[4:5]
	s_add_u32 m0, s10, 0x8800
	ds_read_b128 v[188:191], v139 offset:4096
	global_load_lds_dwordx4 v202, s[4:5]
	s_add_u32 m0, s10, 0x8c00
	ds_read_b128 v[196:199], v143 offset:4096
	global_load_lds_dwordx4 v203, s[4:5]
	s_add_u32 m0, s10, 0xc000
	s_add_u32 s4, s4, 128
	s_addc_u32 s5, s5, 0
	global_load_lds_dwordx4 v200, s[8:9]
	s_add_u32 m0, s10, 0xc400
	s_nop 0
	global_load_lds_dwordx4 v201, s[8:9]
	s_add_u32 m0, s10, 0xc800
	s_nop 0
	global_load_lds_dwordx4 v202, s[8:9]
	s_add_u32 m0, s10, 0xcc00
	s_nop 0
	global_load_lds_dwordx4 v203, s[8:9]
	s_add_u32 s8, s8, 128
	s_addc_u32 s9, s9, 0
	s_waitcnt lgkmcnt(4)
	v_mfma_f32_32x32x16_bf16 v[66:81], v[232:235], v[224:227], v[66:81]
	v_mfma_f32_32x32x16_bf16 v[82:97], v[236:239], v[224:227], v[82:97]
	v_mfma_f32_32x32x16_bf16 v[98:113], v[232:235], v[228:231], v[98:113]
	v_mfma_f32_32x32x16_bf16 v[114:129], v[236:239], v[228:231], v[114:129]
	ds_read_b128 v[224:227], v140 offset:0
	ds_read_b128 v[232:235], v144 offset:0
	ds_read_b128 v[228:231], v140 offset:4096
	ds_read_b128 v[236:239], v144 offset:4096
	s_waitcnt lgkmcnt(4)
	v_mfma_f32_32x32x16_bf16 v[66:81], v[192:195], v[240:243], v[66:81]
	v_mfma_f32_32x32x16_bf16 v[82:97], v[196:199], v[240:243], v[82:97]
	v_mfma_f32_32x32x16_bf16 v[98:113], v[192:195], v[188:191], v[98:113]
	v_mfma_f32_32x32x16_bf16 v[114:129], v[196:199], v[188:191], v[114:129]
	ds_read_b128 v[240:243], v141 offset:0
	ds_read_b128 v[192:195], v145 offset:0
	ds_read_b128 v[188:191], v141 offset:4096
	ds_read_b128 v[196:199], v145 offset:4096
	s_waitcnt lgkmcnt(4)
	v_mfma_f32_32x32x16_bf16 v[66:81], v[232:235], v[224:227], v[66:81]
	v_mfma_f32_32x32x16_bf16 v[82:97], v[236:239], v[224:227], v[82:97]
	v_mfma_f32_32x32x16_bf16 v[98:113], v[232:235], v[228:231], v[98:113]
	v_mfma_f32_32x32x16_bf16 v[114:129], v[236:239], v[228:231], v[114:129]
	s_waitcnt vmcnt(0) lgkmcnt(0)
	s_barrier
; #define G_STORE(S, bf) { *(uint4*)&s->a[bf][srow][skc] = S##a0; *(uint4*)&s->a[bf][srow + 32][skc] = S##a1; \
;     if (MB == 2) { *(uint4*)&s->a[bf][srow + 64][skc] = S##a2; *(uint4*)&s->a[bf][srow + 96][skc] = S##a3; } \
;     *(uint4*)&s->b[bf][srow][skc] = S##b0; *(uint4*)&s->b[bf][srow + 32][skc] = S##b1; *(uint4*)&s->b[bf][srow + 64][skc] = S##b2; *(uint4*)&s->b[bf][srow + 96][skc] = S##b3; }
; template <int MB, bool PF2 = true>
; DI void gemm_main(const u16* __restrict__ A, int lda, const u16* __restrict__ B, int ldb, int K, f32x16 (&acc)[MB][2], GemmLds* s, int tid) {
;     ...
;   for (int kt = 0; kt < KT; kt += 2) {
;     { const int k2 = min((kt + 2) * 64, klast); G_LOAD(q, k2); }
;     __builtin_amdgcn_sched_barrier(0);
;     G_COMPUTE(0);
;     G_STORE(p, 1);
;     __syncthreads();
;     { const int k3 = min((kt + 3) * 64, klast); G_LOAD(p, k3); }
;     __builtin_amdgcn_sched_barrier(0);
;     G_COMPUTE(1);
;     G_STORE(q, 0);
;     __syncthreads();
;   }
; DI void phase_merge(const Params& p, int l, char* smem, int tid) {
;     ...
;       gemm_main<1>(p.G + (size_t)m0 * 1024 + i * 256, 1024, p.WtBr + ((size_t)l * 4 + i) * 1024 * 256 + (size_t)n0 * 256, 256, 256, t, s, tid);
	ds_read_b128 v[224:227], v138 offset:32768
	ds_read_b128 v[232:235], v142 offset:32768
	ds_read_b128 v[228:231], v138 offset:36864
	ds_read_b128 v[236:239], v142 offset:36864
	v_mfma_f32_32x32x16_bf16 v[66:81], v[192:195], v[240:243], v[66:81]
	v_mfma_f32_32x32x16_bf16 v[82:97], v[196:199], v[240:243], v[82:97]
	v_mfma_f32_32x32x16_bf16 v[98:113], v[192:195], v[188:191], v[98:113]
	v_mfma_f32_32x32x16_bf16 v[114:129], v[196:199], v[188:191], v[114:129]
	s_cmp_eq_u32 s11, 0
	s_cbranch_scc1 .Lmgm_last
	s_add_u32 m0, s10, 0x0
	ds_read_b128 v[240:243], v139 offset:32768
	global_load_lds_dwordx4 v200, s[4:5]
	s_add_u32 m0, s10, 0x400
	ds_read_b128 v[192:195], v143 offset:32768
	global_load_lds_dwordx4 v201, s[4:5]
	s_add_u32 m0, s10, 0x800
	ds_read_b128 v[188:191], v139 offset:36864
	global_load_lds_dwordx4 v202, s[4:5]
	s_add_u32 m0, s10, 0xc00
	ds_read_b128 v[196:199], v143 offset:36864
	global_load_lds_dwordx4 v203, s[4:5]
	s_add_u32 m0, s10, 0x4000
	s_add_u32 s4, s4, 128
	s_addc_u32 s5, s5, 0
	global_load_lds_dwordx4 v200, s[8:9]
	s_add_u32 m0, s10, 0x4400
	s_nop 0
	global_load_lds_dwordx4 v201, s[8:9]
	s_add_u32 m0, s10, 0x4800
	s_nop 0
	global_load_lds_dwordx4 v202, s[8:9]
	s_add_u32 m0, s10, 0x4c00
	s_nop 0
	global_load_lds_dwordx4 v203, s[8:9]
	s_add_u32 s8, s8, 128
	s_addc_u32 s9, s9, 0
	s_waitcnt lgkmcnt(4)
	v_mfma_f32_32x32x16_bf16 v[66:81], v[232:235], v[224:227], v[66:81]
	v_mfma_f32_32x32x16_bf16 v[82:97], v[236:239], v[224:227], v[82:97]
	v_mfma_f32_32x32x16_bf16 v[98:113], v[232:235], v[228:231], v[98:113]
	v_mfma_f32_32x32x16_bf16 v[114:129], v[236:239], v[228:231], v[114:129]
	ds_read_b128 v[224:227], v140 offset:32768
	ds_read_b128 v[232:235], v144 offset:32768
	ds_read_b128 v[228:231], v140 offset:36864
	ds_read_b128 v[236:239], v144 offset:36864
	s_waitcnt lgkmcnt(4)
	v_mfma_f32_32x32x16_bf16 v[66:81], v[192:195], v[240:243], v[66:81]
	v_mfma_f32_32x32x16_bf16 v[82:97], v[196:199], v[240:243], v[82:97]
	v_mfma_f32_32x32x16_bf16 v[98:113], v[192:195], v[188:191], v[98:113]
	v_mfma_f32_32x32x16_bf16 v[114:129], v[196:199], v[188:191], v[114:129]
	ds_read_b128 v[240:243], v141 offset:32768
	ds_read_b128 v[192:195], v145 offset:32768
	ds_read_b128 v[188:191], v141 offset:36864
	ds_read_b128 v[196:199], v145 offset:36864
	s_waitcnt lgkmcnt(4)
	v_mfma_f32_32x32x16_bf16 v[66:81], v[232:235], v[224:227], v[66:81]
	v_mfma_f32_32x32x16_bf16 v[82:97], v[236:239], v[224:227], v[82:97]
	v_mfma_f32_32x32x16_bf16 v[98:113], v[232:235], v[228:231], v[98:113]
	v_mfma_f32_32x32x16_bf16 v[114:129], v[236:239], v[228:231], v[114:129]
	s_waitcnt vmcnt(0) lgkmcnt(0)
	s_barrier
	ds_read_b128 v[224:227], v138 offset:0
	ds_read_b128 v[232:235], v142 offset:0
	ds_read_b128 v[228:231], v138 offset:4096
	ds_read_b128 v[236:239], v142 offset:4096
	v_mfma_f32_32x32x16_bf16 v[66:81], v[192:195], v[240:243], v[66:81]
	v_mfma_f32_32x32x16_bf16 v[82:97], v[196:199], v[240:243], v[82:97]
	v_mfma_f32_32x32x16_bf16 v[98:113], v[192:195], v[188:191], v[98:113]
	v_mfma_f32_32x32x16_bf16 v[114:129], v[196:199], v[188:191], v[114:129]
	s_sub_u32 s11, s11, 1
	s_branch .Lmgm_loop
.Lmgm_last:
	s_lshr_b32 s6, s13, 1
	s_lshl_b32 s7, s6, 9
	s_add_u32 s4, s2, 0x16720000
	s_addc_u32 s5, s3, 0
	s_add_u32 s4, s4, s7
	s_addc_u32 s5, s5, 0
	s_lshl_b32 s7, s6, 19
	s_lshr_b32 s8, s19, 2
	s_add_u32 s7, s7, s8
	s_add_u32 s8, s16, s7
	s_addc_u32 s9, s17, 0
	s_add_u32 m0, s10, 0x0
	s_nop 0
	global_load_lds_dwordx4 v200, s[4:5]
	s_add_u32 m0, s10, 0x400
	s_nop 0
	global_load_lds_dwordx4 v201, s[4:5]
	s_add_u32 m0, s10, 0x800
	s_nop 0
	global_load_lds_dwordx4 v202, s[4:5]
	s_add_u32 m0, s10, 0xc00
	s_nop 0
	global_load_lds_dwordx4 v203, s[4:5]
	s_add_u32 m0, s10, 0x4000
	s_nop 0
	global_load_lds_dwordx4 v130, s[8:9]
	s_add_u32 m0, s10, 0x4400
	s_nop 0
	global_load_lds_dwordx4 v131, s[8:9]
	s_add_u32 m0, s10, 0x4800
	s_nop 0
	global_load_lds_dwordx4 v132, s[8:9]
	s_add_u32 m0, s10, 0x4c00
	s_nop 0
	global_load_lds_dwordx4 v133, s[8:9]
	s_add_u32 s4, s4, 128
	s_addc_u32 s5, s5, 0
	s_add_u32 s8, s8, 128
	s_addc_u32 s9, s9, 0
.Lmgm_nopf:
	ds_read_b128 v[240:243], v139 offset:32768
	ds_read_b128 v[192:195], v143 offset:32768
	ds_read_b128 v[188:191], v139 offset:36864
	ds_read_b128 v[196:199], v143 offset:36864
	s_waitcnt lgkmcnt(4)
	v_mfma_f32_32x32x16_bf16 v[66:81], v[232:235], v[224:227], v[66:81]
	v_mfma_f32_32x32x16_bf16 v[82:97], v[236:239], v[224:227], v[82:97]
	v_mfma_f32_32x32x16_bf16 v[98:113], v[232:235], v[228:231], v[98:113]
	v_mfma_f32_32x32x16_bf16 v[114:129], v[236:239], v[228:231], v[114:129]
	ds_read_b128 v[224:227], v140 offset:32768
	ds_read_b128 v[232:235], v144 offset:32768
	ds_read_b128 v[228:231], v140 offset:36864
	ds_read_b128 v[236:239], v144 offset:36864
	s_waitcnt lgkmcnt(4)
	v_mfma_f32_32x32x16_bf16 v[66:81], v[192:195], v[240:243], v[66:81]
	v_mfma_f32_32x32x16_bf16 v[82:97], v[196:199], v[240:243], v[82:97]
	v_mfma_f32_32x32x16_bf16 v[98:113], v[192:195], v[188:191], v[98:113]
	v_mfma_f32_32x32x16_bf16 v[114:129], v[196:199], v[188:191], v[114:129]
	ds_read_b128 v[240:243], v141 offset:32768
	ds_read_b128 v[192:195], v145 offset:32768
	ds_read_b128 v[188:191], v141 offset:36864
	ds_read_b128 v[196:199], v145 offset:36864
	s_waitcnt lgkmcnt(4)
	v_mfma_f32_32x32x16_bf16 v[66:81], v[232:235], v[224:227], v[66:81]
	v_mfma_f32_32x32x16_bf16 v[82:97], v[236:239], v[224:227], v[82:97]
	v_mfma_f32_32x32x16_bf16 v[98:113], v[232:235], v[228:231], v[98:113]
	v_mfma_f32_32x32x16_bf16 v[114:129], v[236:239], v[228:231], v[114:129]
	s_waitcnt lgkmcnt(0)
	s_barrier
; DI unsigned pack2(float a, float b) { f32v2 v = {a, b}; return __builtin_bit_cast(unsigned, __builtin_convertvector(v, bf16v2)); }
; DI float sigm_fast(float x) { return __builtin_amdgcn_rcpf(1.f + __expf(-x)); }
; DI void phase_merge(const Params& p, int l, char* smem, int tid) {
;     ...
; #pragma unroll
;         for (int b2 = 0; b2 < 2; b2++)
; #pragma unroll
;           for (int e = 0; e < 8; e++) sg[b2][e] = pack2(sigm_fast(m[0][b2][2 * e]), sigm_fast(m[0][b2][2 * e + 1]));
	v_mfma_f32_32x32x16_bf16 v[66:81], v[192:195], v[240:243], v[66:81]
	v_mfma_f32_32x32x16_bf16 v[82:97], v[196:199], v[240:243], v[82:97]
	v_mfma_f32_32x32x16_bf16 v[98:113], v[192:195], v[188:191], v[98:113]
	v_mfma_f32_32x32x16_bf16 v[114:129], v[196:199], v[188:191], v[114:129]
	s_nop 7
	s_nop 7
	v_mul_f32_e32 v66, 0xbfb8aa3b, v66
	v_mul_f32_e32 v67, 0xbfb8aa3b, v67
	v_mul_f32_e32 v68, 0xbfb8aa3b, v68
	v_mul_f32_e32 v69, 0xbfb8aa3b, v69
	v_mul_f32_e32 v70, 0xbfb8aa3b, v70
	v_mul_f32_e32 v71, 0xbfb8aa3b, v71
	v_mul_f32_e32 v72, 0xbfb8aa3b, v72
	v_mul_f32_e32 v73, 0xbfb8aa3b, v73
	v_exp_f32_e32 v66, v66
	v_exp_f32_e32 v67, v67
	v_exp_f32_e32 v68, v68
	v_exp_f32_e32 v69, v69
	v_exp_f32_e32 v70, v70
	v_exp_f32_e32 v71, v71
	v_exp_f32_e32 v72, v72
	v_exp_f32_e32 v73, v73
	v_add_f32_e32 v66, 1.0, v66
	v_add_f32_e32 v67, 1.0, v67
	v_add_f32_e32 v68, 1.0, v68
	v_add_f32_e32 v69, 1.0, v69
	v_add_f32_e32 v70, 1.0, v70
	v_add_f32_e32 v71, 1.0, v71
	v_add_f32_e32 v72, 1.0, v72
	v_add_f32_e32 v73, 1.0, v73
	v_rcp_f32_e32 v66, v66
	v_rcp_f32_e32 v67, v67
	v_rcp_f32_e32 v68, v68
	v_rcp_f32_e32 v69, v69
	v_rcp_f32_e32 v70, v70
	v_rcp_f32_e32 v71, v71
	v_rcp_f32_e32 v72, v72
	v_rcp_f32_e32 v73, v73
	s_nop 0
	v_cvt_pk_bf16_f32 v156, v66, v67
	v_cvt_pk_bf16_f32 v157, v68, v69
	v_cvt_pk_bf16_f32 v158, v70, v71
	v_cvt_pk_bf16_f32 v159, v72, v73
	v_mul_f32_e32 v74, 0xbfb8aa3b, v74
	v_mul_f32_e32 v75, 0xbfb8aa3b, v75
	v_mul_f32_e32 v76, 0xbfb8aa3b, v76
	v_mul_f32_e32 v77, 0xbfb8aa3b, v77
	v_mul_f32_e32 v78, 0xbfb8aa3b, v78
	v_mul_f32_e32 v79, 0xbfb8aa3b, v79
	v_mul_f32_e32 v80, 0xbfb8aa3b, v80
	v_mul_f32_e32 v81, 0xbfb8aa3b, v81
	v_exp_f32_e32 v74, v74
	v_exp_f32_e32 v75, v75
	v_exp_f32_e32 v76, v76
	v_exp_f32_e32 v77, v77
	v_exp_f32_e32 v78, v78
	v_exp_f32_e32 v79, v79
	v_exp_f32_e32 v80, v80
	v_exp_f32_e32 v81, v81
	v_add_f32_e32 v74, 1.0, v74
	v_add_f32_e32 v75, 1.0, v75
	v_add_f32_e32 v76, 1.0, v76
	v_add_f32_e32 v77, 1.0, v77
	v_add_f32_e32 v78, 1.0, v78
	v_add_f32_e32 v79, 1.0, v79
	v_add_f32_e32 v80, 1.0, v80
	v_add_f32_e32 v81, 1.0, v81
	v_rcp_f32_e32 v74, v74
	v_rcp_f32_e32 v75, v75
	v_rcp_f32_e32 v76, v76
	v_rcp_f32_e32 v77, v77
	v_rcp_f32_e32 v78, v78
	v_rcp_f32_e32 v79, v79
	v_rcp_f32_e32 v80, v80
	v_rcp_f32_e32 v81, v81
	s_nop 0
	v_cvt_pk_bf16_f32 v160, v74, v75
	v_cvt_pk_bf16_f32 v161, v76, v77
	v_cvt_pk_bf16_f32 v162, v78, v79
	v_cvt_pk_bf16_f32 v163, v80, v81
	v_mul_f32_e32 v82, 0xbfb8aa3b, v82
	v_mul_f32_e32 v83, 0xbfb8aa3b, v83
	v_mul_f32_e32 v84, 0xbfb8aa3b, v84
	v_mul_f32_e32 v85, 0xbfb8aa3b, v85
	v_mul_f32_e32 v86, 0xbfb8aa3b, v86
	v_mul_f32_e32 v87, 0xbfb8aa3b, v87
	v_mul_f32_e32 v88, 0xbfb8aa3b, v88
	v_mul_f32_e32 v89, 0xbfb8aa3b, v89
	v_exp_f32_e32 v82, v82
	v_exp_f32_e32 v83, v83
	v_exp_f32_e32 v84, v84
	v_exp_f32_e32 v85, v85
	v_exp_f32_e32 v86, v86
	v_exp_f32_e32 v87, v87
	v_exp_f32_e32 v88, v88
	v_exp_f32_e32 v89, v89
	v_add_f32_e32 v82, 1.0, v82
	v_add_f32_e32 v83, 1.0, v83
	v_add_f32_e32 v84, 1.0, v84
	v_add_f32_e32 v85, 1.0, v85
	v_add_f32_e32 v86, 1.0, v86
	v_add_f32_e32 v87, 1.0, v87
	v_add_f32_e32 v88, 1.0, v88
	v_add_f32_e32 v89, 1.0, v89
	v_rcp_f32_e32 v82, v82
	v_rcp_f32_e32 v83, v83
	v_rcp_f32_e32 v84, v84
	v_rcp_f32_e32 v85, v85
	v_rcp_f32_e32 v86, v86
	v_rcp_f32_e32 v87, v87
	v_rcp_f32_e32 v88, v88
	v_rcp_f32_e32 v89, v89
	s_nop 0
	v_cvt_pk_bf16_f32 v164, v82, v83
	v_cvt_pk_bf16_f32 v165, v84, v85
	v_cvt_pk_bf16_f32 v166, v86, v87
	v_cvt_pk_bf16_f32 v167, v88, v89
	v_mul_f32_e32 v90, 0xbfb8aa3b, v90
	v_mul_f32_e32 v91, 0xbfb8aa3b, v91
	v_mul_f32_e32 v92, 0xbfb8aa3b, v92
	v_mul_f32_e32 v93, 0xbfb8aa3b, v93
	v_mul_f32_e32 v94, 0xbfb8aa3b, v94
	v_mul_f32_e32 v95, 0xbfb8aa3b, v95
	v_mul_f32_e32 v96, 0xbfb8aa3b, v96
	v_mul_f32_e32 v97, 0xbfb8aa3b, v97
	v_exp_f32_e32 v90, v90
	v_exp_f32_e32 v91, v91
	v_exp_f32_e32 v92, v92
	v_exp_f32_e32 v93, v93
	v_exp_f32_e32 v94, v94
	v_exp_f32_e32 v95, v95
	v_exp_f32_e32 v96, v96
	v_exp_f32_e32 v97, v97
	v_add_f32_e32 v90, 1.0, v90
	v_add_f32_e32 v91, 1.0, v91
	v_add_f32_e32 v92, 1.0, v92
	v_add_f32_e32 v93, 1.0, v93
	v_add_f32_e32 v94, 1.0, v94
	v_add_f32_e32 v95, 1.0, v95
	v_add_f32_e32 v96, 1.0, v96
	v_add_f32_e32 v97, 1.0, v97
	v_rcp_f32_e32 v90, v90
	v_rcp_f32_e32 v91, v91
	v_rcp_f32_e32 v92, v92
	v_rcp_f32_e32 v93, v93
	v_rcp_f32_e32 v94, v94
	v_rcp_f32_e32 v95, v95
	v_rcp_f32_e32 v96, v96
	v_rcp_f32_e32 v97, v97
	s_nop 0
	v_cvt_pk_bf16_f32 v168, v90, v91
	v_cvt_pk_bf16_f32 v169, v92, v93
	v_cvt_pk_bf16_f32 v170, v94, v95
	v_cvt_pk_bf16_f32 v171, v96, v97
	v_mul_f32_e32 v98, 0xbfb8aa3b, v98
	v_mul_f32_e32 v99, 0xbfb8aa3b, v99
	v_mul_f32_e32 v100, 0xbfb8aa3b, v100
	v_mul_f32_e32 v101, 0xbfb8aa3b, v101
	v_mul_f32_e32 v102, 0xbfb8aa3b, v102
	v_mul_f32_e32 v103, 0xbfb8aa3b, v103
	v_mul_f32_e32 v104, 0xbfb8aa3b, v104
	v_mul_f32_e32 v105, 0xbfb8aa3b, v105
	v_exp_f32_e32 v98, v98
	v_exp_f32_e32 v99, v99
	v_exp_f32_e32 v100, v100
	v_exp_f32_e32 v101, v101
	v_exp_f32_e32 v102, v102
	v_exp_f32_e32 v103, v103
	v_exp_f32_e32 v104, v104
	v_exp_f32_e32 v105, v105
	v_add_f32_e32 v98, 1.0, v98
	v_add_f32_e32 v99, 1.0, v99
	v_add_f32_e32 v100, 1.0, v100
	v_add_f32_e32 v101, 1.0, v101
	v_add_f32_e32 v102, 1.0, v102
	v_add_f32_e32 v103, 1.0, v103
	v_add_f32_e32 v104, 1.0, v104
	v_add_f32_e32 v105, 1.0, v105
	v_rcp_f32_e32 v98, v98
	v_rcp_f32_e32 v99, v99
	v_rcp_f32_e32 v100, v100
	v_rcp_f32_e32 v101, v101
	v_rcp_f32_e32 v102, v102
	v_rcp_f32_e32 v103, v103
	v_rcp_f32_e32 v104, v104
	v_rcp_f32_e32 v105, v105
	s_nop 0
	v_cvt_pk_bf16_f32 v172, v98, v99
	v_cvt_pk_bf16_f32 v173, v100, v101
	v_cvt_pk_bf16_f32 v174, v102, v103
	v_cvt_pk_bf16_f32 v175, v104, v105
	v_mul_f32_e32 v106, 0xbfb8aa3b, v106
; DI unsigned pack2(float a, float b) { f32v2 v = {a, b}; return __builtin_bit_cast(unsigned, __builtin_convertvector(v, bf16v2)); }
; DI float sigm_fast(float x) { return __builtin_amdgcn_rcpf(1.f + __expf(-x)); }
; template <int MB>
; DI void zero_acc(f32x16 (&acc)[MB][2]) {
; #pragma unroll
;   for (int a = 0; a < MB; a++)
; #pragma unroll
;     for (int b = 0; b < 2; b++)
; #pragma unroll
;       for (int i = 0; i < 16; i++) acc[a][b][i] = 0.f;
; DI void phase_merge(const Params& p, int l, char* smem, int tid) {
;     ...
;           for (int e = 0; e < 8; e++) sg[b2][e] = pack2(sigm_fast(m[0][b2][2 * e]), sigm_fast(m[0][b2][2 * e + 1]));
;       }
;       f32x16 t[1][2]; zero_acc<1>(t);
;       gemm_main<1>(p.G + (size_t)m0 * 1024 + i * 256, 1024, p.WtBr + ((size_t)l * 4 + i) * 1024 * 256 + (size_t)n0 * 256, 256, 256, t, s, tid);
	v_mul_f32_e32 v107, 0xbfb8aa3b, v107
	v_mul_f32_e32 v108, 0xbfb8aa3b, v108
	v_mul_f32_e32 v109, 0xbfb8aa3b, v109
	v_mul_f32_e32 v110, 0xbfb8aa3b, v110
	v_mul_f32_e32 v111, 0xbfb8aa3b, v111
	v_mul_f32_e32 v112, 0xbfb8aa3b, v112
	v_mul_f32_e32 v113, 0xbfb8aa3b, v113
	v_exp_f32_e32 v106, v106
	v_exp_f32_e32 v107, v107
	v_exp_f32_e32 v108, v108
	v_exp_f32_e32 v109, v109
	v_exp_f32_e32 v110, v110
	v_exp_f32_e32 v111, v111
	v_exp_f32_e32 v112, v112
	v_exp_f32_e32 v113, v113
	v_add_f32_e32 v106, 1.0, v106
	v_add_f32_e32 v107, 1.0, v107
	v_add_f32_e32 v108, 1.0, v108
	v_add_f32_e32 v109, 1.0, v109
	v_add_f32_e32 v110, 1.0, v110
	v_add_f32_e32 v111, 1.0, v111
	v_add_f32_e32 v112, 1.0, v112
	v_add_f32_e32 v113, 1.0, v113
	v_rcp_f32_e32 v106, v106
	v_rcp_f32_e32 v107, v107
	v_rcp_f32_e32 v108, v108
	v_rcp_f32_e32 v109, v109
	v_rcp_f32_e32 v110, v110
	v_rcp_f32_e32 v111, v111
	v_rcp_f32_e32 v112, v112
	v_rcp_f32_e32 v113, v113
	s_nop 0
	v_cvt_pk_bf16_f32 v176, v106, v107
	v_cvt_pk_bf16_f32 v177, v108, v109
	v_cvt_pk_bf16_f32 v178, v110, v111
	v_cvt_pk_bf16_f32 v179, v112, v113
	v_mul_f32_e32 v114, 0xbfb8aa3b, v114
	v_mul_f32_e32 v115, 0xbfb8aa3b, v115
	v_mul_f32_e32 v116, 0xbfb8aa3b, v116
	v_mul_f32_e32 v117, 0xbfb8aa3b, v117
	v_mul_f32_e32 v118, 0xbfb8aa3b, v118
	v_mul_f32_e32 v119, 0xbfb8aa3b, v119
	v_mul_f32_e32 v120, 0xbfb8aa3b, v120
	v_mul_f32_e32 v121, 0xbfb8aa3b, v121
	v_exp_f32_e32 v114, v114
	v_exp_f32_e32 v115, v115
	v_exp_f32_e32 v116, v116
	v_exp_f32_e32 v117, v117
	v_exp_f32_e32 v118, v118
	v_exp_f32_e32 v119, v119
	v_exp_f32_e32 v120, v120
	v_exp_f32_e32 v121, v121
	v_add_f32_e32 v114, 1.0, v114
	v_add_f32_e32 v115, 1.0, v115
	v_add_f32_e32 v116, 1.0, v116
	v_add_f32_e32 v117, 1.0, v117
	v_add_f32_e32 v118, 1.0, v118
	v_add_f32_e32 v119, 1.0, v119
	v_add_f32_e32 v120, 1.0, v120
	v_add_f32_e32 v121, 1.0, v121
	v_rcp_f32_e32 v114, v114
	v_rcp_f32_e32 v115, v115
	v_rcp_f32_e32 v116, v116
	v_rcp_f32_e32 v117, v117
	v_rcp_f32_e32 v118, v118
	v_rcp_f32_e32 v119, v119
	v_rcp_f32_e32 v120, v120
	v_rcp_f32_e32 v121, v121
	s_nop 0
	v_cvt_pk_bf16_f32 v180, v114, v115
	v_cvt_pk_bf16_f32 v181, v116, v117
	v_cvt_pk_bf16_f32 v182, v118, v119
	v_cvt_pk_bf16_f32 v183, v120, v121
	v_mul_f32_e32 v122, 0xbfb8aa3b, v122
	v_mul_f32_e32 v123, 0xbfb8aa3b, v123
	v_mul_f32_e32 v124, 0xbfb8aa3b, v124
	v_mul_f32_e32 v125, 0xbfb8aa3b, v125
	v_mul_f32_e32 v126, 0xbfb8aa3b, v126
	v_mul_f32_e32 v127, 0xbfb8aa3b, v127
	v_mul_f32_e32 v128, 0xbfb8aa3b, v128
	v_mul_f32_e32 v129, 0xbfb8aa3b, v129
	v_exp_f32_e32 v122, v122
	v_exp_f32_e32 v123, v123
	v_exp_f32_e32 v124, v124
	v_exp_f32_e32 v125, v125
	v_exp_f32_e32 v126, v126
	v_exp_f32_e32 v127, v127
	v_exp_f32_e32 v128, v128
	v_exp_f32_e32 v129, v129
	v_add_f32_e32 v122, 1.0, v122
	v_add_f32_e32 v123, 1.0, v123
	v_add_f32_e32 v124, 1.0, v124
	v_add_f32_e32 v125, 1.0, v125
	v_add_f32_e32 v126, 1.0, v126
	v_add_f32_e32 v127, 1.0, v127
	v_add_f32_e32 v128, 1.0, v128
	v_add_f32_e32 v129, 1.0, v129
	v_rcp_f32_e32 v122, v122
	v_rcp_f32_e32 v123, v123
	v_rcp_f32_e32 v124, v124
	v_rcp_f32_e32 v125, v125
	v_rcp_f32_e32 v126, v126
	v_rcp_f32_e32 v127, v127
	v_rcp_f32_e32 v128, v128
	v_rcp_f32_e32 v129, v129
	s_nop 0
	v_cvt_pk_bf16_f32 v184, v122, v123
	v_cvt_pk_bf16_f32 v185, v124, v125
	v_cvt_pk_bf16_f32 v186, v126, v127
	v_cvt_pk_bf16_f32 v187, v128, v129
	s_add_u32 s13, s13, 1
	v_mov_b32_e32 v66, 0
	v_mov_b32_e32 v67, 0
	v_mov_b32_e32 v68, 0
	v_mov_b32_e32 v69, 0
	v_mov_b32_e32 v70, 0
	v_mov_b32_e32 v71, 0
	v_mov_b32_e32 v72, 0
	v_mov_b32_e32 v73, 0
	v_mov_b32_e32 v74, 0
	v_mov_b32_e32 v75, 0
	v_mov_b32_e32 v76, 0
	v_mov_b32_e32 v77, 0
	v_mov_b32_e32 v78, 0
	v_mov_b32_e32 v79, 0
	v_mov_b32_e32 v80, 0
	v_mov_b32_e32 v81, 0
	v_mov_b32_e32 v82, 0
	v_mov_b32_e32 v83, 0
	v_mov_b32_e32 v84, 0
	v_mov_b32_e32 v85, 0
	v_mov_b32_e32 v86, 0
	v_mov_b32_e32 v87, 0
	v_mov_b32_e32 v88, 0
	v_mov_b32_e32 v89, 0
	v_mov_b32_e32 v90, 0
	v_mov_b32_e32 v91, 0
	v_mov_b32_e32 v92, 0
	v_mov_b32_e32 v93, 0
	v_mov_b32_e32 v94, 0
	v_mov_b32_e32 v95, 0
	v_mov_b32_e32 v96, 0
	v_mov_b32_e32 v97, 0
	v_mov_b32_e32 v98, 0
	v_mov_b32_e32 v99, 0
	v_mov_b32_e32 v100, 0
	v_mov_b32_e32 v101, 0
	v_mov_b32_e32 v102, 0
	v_mov_b32_e32 v103, 0
	v_mov_b32_e32 v104, 0
	v_mov_b32_e32 v105, 0
	v_mov_b32_e32 v106, 0
	v_mov_b32_e32 v107, 0
	v_mov_b32_e32 v108, 0
	v_mov_b32_e32 v109, 0
	v_mov_b32_e32 v110, 0
	v_mov_b32_e32 v111, 0
	v_mov_b32_e32 v112, 0
	v_mov_b32_e32 v113, 0
	v_mov_b32_e32 v114, 0
	v_mov_b32_e32 v115, 0
	v_mov_b32_e32 v116, 0
	v_mov_b32_e32 v117, 0
	v_mov_b32_e32 v118, 0
	v_mov_b32_e32 v119, 0
	v_mov_b32_e32 v120, 0
	v_mov_b32_e32 v121, 0
	v_mov_b32_e32 v122, 0
	v_mov_b32_e32 v123, 0
	v_mov_b32_e32 v124, 0
	v_mov_b32_e32 v125, 0
	v_mov_b32_e32 v126, 0
	v_mov_b32_e32 v127, 0
	v_mov_b32_e32 v128, 0
	v_mov_b32_e32 v129, 0
	s_waitcnt vmcnt(0) lgkmcnt(0)
	s_barrier
	ds_read_b128 v[224:227], v138 offset:0
	ds_read_b128 v[232:235], v142 offset:0
	ds_read_b128 v[228:231], v138 offset:4096
	ds_read_b128 v[236:239], v142 offset:4096
	s_mov_b32 s11, 1
; #define G_STORE(S, bf) { *(uint4*)&s->a[bf][srow][skc] = S##a0; *(uint4*)&s->a[bf][srow + 32][skc] = S##a1; \
;     if (MB == 2) { *(uint4*)&s->a[bf][srow + 64][skc] = S##a2; *(uint4*)&s->a[bf][srow + 96][skc] = S##a3; } \
;     *(uint4*)&s->b[bf][srow][skc] = S##b0; *(uint4*)&s->b[bf][srow + 32][skc] = S##b1; *(uint4*)&s->b[bf][srow + 64][skc] = S##b2; *(uint4*)&s->b[bf][srow + 96][skc] = S##b3; }
; template <int MB, bool PF2 = true>
; DI void gemm_main(const u16* __restrict__ A, int lda, const u16* __restrict__ B, int ldb, int K, f32x16 (&acc)[MB][2], GemmLds* s, int tid) {
;     ...
;   for (int kt = 0; kt < KT; kt += 2) {
;     { const int k2 = min((kt + 2) * 64, klast); G_LOAD(q, k2); }
;     __builtin_amdgcn_sched_barrier(0);
;     G_COMPUTE(0);
;     G_STORE(p, 1);
;     __syncthreads();
;     { const int k3 = min((kt + 3) * 64, klast); G_LOAD(p, k3); }
;     __builtin_amdgcn_sched_barrier(0);
;     G_COMPUTE(1);
;     G_STORE(q, 0);
;     __syncthreads();
;   }
.Lmgt_loop:
	s_add_u32 m0, s10, 0x8000
	ds_read_b128 v[240:243], v139 offset:0
	global_load_lds_dwordx4 v200, s[4:5]
	s_add_u32 m0, s10, 0x8400
	ds_read_b128 v[192:195], v143 offset:0
	global_load_lds_dwordx4 v201, s[4:5]
	s_add_u32 m0, s10, 0x8800
	ds_read_b128 v[188:191], v139 offset:4096
	global_load_lds_dwordx4 v202, s[4:5]
	s_add_u32 m0, s10, 0x8c00
	ds_read_b128 v[196:199], v143 offset:4096
	global_load_lds_dwordx4 v203, s[4:5]
	s_add_u32 m0, s10, 0xc000
	s_add_u32 s4, s4, 128
	s_addc_u32 s5, s5, 0
	global_load_lds_dwordx4 v130, s[8:9]
	s_add_u32 m0, s10, 0xc400
	s_nop 0
	global_load_lds_dwordx4 v131, s[8:9]
	s_add_u32 m0, s10, 0xc800
	s_nop 0
	global_load_lds_dwordx4 v132, s[8:9]
	s_add_u32 m0, s10, 0xcc00
	s_nop 0
	global_load_lds_dwordx4 v133, s[8:9]
	s_add_u32 s8, s8, 128
	s_addc_u32 s9, s9, 0
	s_waitcnt lgkmcnt(4)
	v_mfma_f32_32x32x16_bf16 v[66:81], v[232:235], v[224:227], v[66:81]
	v_mfma_f32_32x32x16_bf16 v[82:97], v[236:239], v[224:227], v[82:97]
	v_mfma_f32_32x32x16_bf16 v[98:113], v[232:235], v[228:231], v[98:113]
	v_mfma_f32_32x32x16_bf16 v[114:129], v[236:239], v[228:231], v[114:129]
	ds_read_b128 v[224:227], v140 offset:0
	ds_read_b128 v[232:235], v144 offset:0
	ds_read_b128 v[228:231], v140 offset:4096
	ds_read_b128 v[236:239], v144 offset:4096
	s_waitcnt lgkmcnt(4)
	v_mfma_f32_32x32x16_bf16 v[66:81], v[192:195], v[240:243], v[66:81]
	v_mfma_f32_32x32x16_bf16 v[82:97], v[196:199], v[240:243], v[82:97]
	v_mfma_f32_32x32x16_bf16 v[98:113], v[192:195], v[188:191], v[98:113]
	v_mfma_f32_32x32x16_bf16 v[114:129], v[196:199], v[188:191], v[114:129]
	ds_read_b128 v[240:243], v141 offset:0
	ds_read_b128 v[192:195], v145 offset:0
	ds_read_b128 v[188:191], v141 offset:4096
	ds_read_b128 v[196:199], v145 offset:4096
	s_waitcnt lgkmcnt(4)
	v_mfma_f32_32x32x16_bf16 v[66:81], v[232:235], v[224:227], v[66:81]
	v_mfma_f32_32x32x16_bf16 v[82:97], v[236:239], v[224:227], v[82:97]
	v_mfma_f32_32x32x16_bf16 v[98:113], v[232:235], v[228:231], v[98:113]
	v_mfma_f32_32x32x16_bf16 v[114:129], v[236:239], v[228:231], v[114:129]
	s_waitcnt vmcnt(0) lgkmcnt(0)
	s_barrier
	ds_read_b128 v[224:227], v138 offset:32768
	ds_read_b128 v[232:235], v142 offset:32768
	ds_read_b128 v[228:231], v138 offset:36864
	ds_read_b128 v[236:239], v142 offset:36864
	v_mfma_f32_32x32x16_bf16 v[66:81], v[192:195], v[240:243], v[66:81]
	v_mfma_f32_32x32x16_bf16 v[82:97], v[196:199], v[240:243], v[82:97]
	v_mfma_f32_32x32x16_bf16 v[98:113], v[192:195], v[188:191], v[98:113]
	v_mfma_f32_32x32x16_bf16 v[114:129], v[196:199], v[188:191], v[114:129]
	s_cmp_eq_u32 s11, 0
	s_cbranch_scc1 .Lmgt_last
	s_add_u32 m0, s10, 0x0
	ds_read_b128 v[240:243], v139 offset:32768
	global_load_lds_dwordx4 v200, s[4:5]
	s_add_u32 m0, s10, 0x400
	ds_read_b128 v[192:195], v143 offset:32768
	global_load_lds_dwordx4 v201, s[4:5]
	s_add_u32 m0, s10, 0x800
	ds_read_b128 v[188:191], v139 offset:36864
	global_load_lds_dwordx4 v202, s[4:5]
	s_add_u32 m0, s10, 0xc00
	ds_read_b128 v[196:199], v143 offset:36864
	global_load_lds_dwordx4 v203, s[4:5]
	s_add_u32 m0, s10, 0x4000
	s_add_u32 s4, s4, 128
	s_addc_u32 s5, s5, 0
	global_load_lds_dwordx4 v130, s[8:9]
	s_add_u32 m0, s10, 0x4400
	s_nop 0
	global_load_lds_dwordx4 v131, s[8:9]
	s_add_u32 m0, s10, 0x4800
	s_nop 0
	global_load_lds_dwordx4 v132, s[8:9]
	s_add_u32 m0, s10, 0x4c00
	s_nop 0
	global_load_lds_dwordx4 v133, s[8:9]
	s_add_u32 s8, s8, 128
	s_addc_u32 s9, s9, 0
	s_waitcnt lgkmcnt(4)
	v_mfma_f32_32x32x16_bf16 v[66:81], v[232:235], v[224:227], v[66:81]
	v_mfma_f32_32x32x16_bf16 v[82:97], v[236:239], v[224:227], v[82:97]
	v_mfma_f32_32x32x16_bf16 v[98:113], v[232:235], v[228:231], v[98:113]
	v_mfma_f32_32x32x16_bf16 v[114:129], v[236:239], v[228:231], v[114:129]
	ds_read_b128 v[224:227], v140 offset:32768
	ds_read_b128 v[232:235], v144 offset:32768
	ds_read_b128 v[228:231], v140 offset:36864
	ds_read_b128 v[236:239], v144 offset:36864
	s_waitcnt lgkmcnt(4)
	v_mfma_f32_32x32x16_bf16 v[66:81], v[192:195], v[240:243], v[66:81]
	v_mfma_f32_32x32x16_bf16 v[82:97], v[196:199], v[240:243], v[82:97]
	v_mfma_f32_32x32x16_bf16 v[98:113], v[192:195], v[188:191], v[98:113]
	v_mfma_f32_32x32x16_bf16 v[114:129], v[196:199], v[188:191], v[114:129]
	ds_read_b128 v[240:243], v141 offset:32768
	ds_read_b128 v[192:195], v145 offset:32768
	ds_read_b128 v[188:191], v141 offset:36864
	ds_read_b128 v[196:199], v145 offset:36864
	s_waitcnt lgkmcnt(4)
	v_mfma_f32_32x32x16_bf16 v[66:81], v[232:235], v[224:227], v[66:81]
	v_mfma_f32_32x32x16_bf16 v[82:97], v[236:239], v[224:227], v[82:97]
	v_mfma_f32_32x32x16_bf16 v[98:113], v[232:235], v[228:231], v[98:113]
	v_mfma_f32_32x32x16_bf16 v[114:129], v[236:239], v[228:231], v[114:129]
	s_waitcnt vmcnt(0) lgkmcnt(0)
	s_barrier
	ds_read_b128 v[224:227], v138 offset:0
	ds_read_b128 v[232:235], v142 offset:0
	ds_read_b128 v[228:231], v138 offset:4096
	ds_read_b128 v[236:239], v142 offset:4096
	v_mfma_f32_32x32x16_bf16 v[66:81], v[192:195], v[240:243], v[66:81]
	v_mfma_f32_32x32x16_bf16 v[82:97], v[196:199], v[240:243], v[82:97]
	v_mfma_f32_32x32x16_bf16 v[98:113], v[192:195], v[188:191], v[98:113]
	v_mfma_f32_32x32x16_bf16 v[114:129], v[196:199], v[188:191], v[114:129]
	s_sub_u32 s11, s11, 1
	s_branch .Lmgt_loop
; #define G_STORE(S, bf) { *(uint4*)&s->a[bf][srow][skc] = S##a0; *(uint4*)&s->a[bf][srow + 32][skc] = S##a1; \
;     if (MB == 2) { *(uint4*)&s->a[bf][srow + 64][skc] = S##a2; *(uint4*)&s->a[bf][srow + 96][skc] = S##a3; } \
;     *(uint4*)&s->b[bf][srow][skc] = S##b0; *(uint4*)&s->b[bf][srow + 32][skc] = S##b1; *(uint4*)&s->b[bf][srow + 64][skc] = S##b2; *(uint4*)&s->b[bf][srow + 96][skc] = S##b3; }
; template <int MB, bool PF2 = true>
; DI void gemm_main(const u16* __restrict__ A, int lda, const u16* __restrict__ B, int ldb, int K, f32x16 (&acc)[MB][2], GemmLds* s, int tid) {
;     ...
;   for (int kt = 0; kt < KT; kt += 2) {
;     { const int k2 = min((kt + 2) * 64, klast); G_LOAD(q, k2); }
;     __builtin_amdgcn_sched_barrier(0);
;     G_COMPUTE(0);
;     G_STORE(p, 1);
;     __syncthreads();
;     { const int k3 = min((kt + 3) * 64, klast); G_LOAD(p, k3); }
;     __builtin_amdgcn_sched_barrier(0);
;     G_COMPUTE(1);
;     G_STORE(q, 0);
;     __syncthreads();
;   }
; DI void phase_merge(const Params& p, int l, char* smem, int tid) {
;     ...
;         gemm_main<1>(p.xn + (size_t)m0 * 1024, 1024, p.WtM + (size_t)l * 4096 * 1024 + ((size_t)i * 1024 + n0) * 1024, 1024, 1024, m, s, tid);
.Lmgt_last:
	s_cmp_eq_u32 s13, 7
	s_cbranch_scc1 .Lmgt_nopf
	s_add_u32 s6, s13, 1
	s_lshr_b32 s6, s6, 1
	s_mov_b32 s4, s2
	s_mov_b32 s5, s3
	s_lshl_b32 s7, s6, 21
	s_add_u32 s7, s7, s19
	s_add_u32 s8, s14, s7
	s_addc_u32 s9, s15, 0
	s_add_u32 m0, s10, 0x0
	s_nop 0
	global_load_lds_dwordx4 v200, s[4:5]
	s_add_u32 m0, s10, 0x400
	s_nop 0
	global_load_lds_dwordx4 v201, s[4:5]
	s_add_u32 m0, s10, 0x800
	s_nop 0
	global_load_lds_dwordx4 v202, s[4:5]
	s_add_u32 m0, s10, 0xc00
	s_nop 0
	global_load_lds_dwordx4 v203, s[4:5]
	s_add_u32 m0, s10, 0x4000
	s_nop 0
	global_load_lds_dwordx4 v200, s[8:9]
	s_add_u32 m0, s10, 0x4400
	s_nop 0
	global_load_lds_dwordx4 v201, s[8:9]
	s_add_u32 m0, s10, 0x4800
	s_nop 0
	global_load_lds_dwordx4 v202, s[8:9]
	s_add_u32 m0, s10, 0x4c00
	s_nop 0
	global_load_lds_dwordx4 v203, s[8:9]
	s_add_u32 s4, s4, 128
	s_addc_u32 s5, s5, 0
	s_add_u32 s8, s8, 128
	s_addc_u32 s9, s9, 0
.Lmgt_nopf:
	ds_read_b128 v[240:243], v139 offset:32768
	ds_read_b128 v[192:195], v143 offset:32768
	ds_read_b128 v[188:191], v139 offset:36864
	ds_read_b128 v[196:199], v143 offset:36864
	s_waitcnt lgkmcnt(4)
	v_mfma_f32_32x32x16_bf16 v[66:81], v[232:235], v[224:227], v[66:81]
	v_mfma_f32_32x32x16_bf16 v[82:97], v[236:239], v[224:227], v[82:97]
	v_mfma_f32_32x32x16_bf16 v[98:113], v[232:235], v[228:231], v[98:113]
	v_mfma_f32_32x32x16_bf16 v[114:129], v[236:239], v[228:231], v[114:129]
	ds_read_b128 v[224:227], v140 offset:32768
	ds_read_b128 v[232:235], v144 offset:32768
	ds_read_b128 v[228:231], v140 offset:36864
	ds_read_b128 v[236:239], v144 offset:36864
	s_waitcnt lgkmcnt(4)
	v_mfma_f32_32x32x16_bf16 v[66:81], v[192:195], v[240:243], v[66:81]
	v_mfma_f32_32x32x16_bf16 v[82:97], v[196:199], v[240:243], v[82:97]
	v_mfma_f32_32x32x16_bf16 v[98:113], v[192:195], v[188:191], v[98:113]
	v_mfma_f32_32x32x16_bf16 v[114:129], v[196:199], v[188:191], v[114:129]
	ds_read_b128 v[240:243], v141 offset:32768
	ds_read_b128 v[192:195], v145 offset:32768
	ds_read_b128 v[188:191], v141 offset:36864
	ds_read_b128 v[196:199], v145 offset:36864
	s_waitcnt lgkmcnt(4)
	v_mfma_f32_32x32x16_bf16 v[66:81], v[232:235], v[224:227], v[66:81]
	v_mfma_f32_32x32x16_bf16 v[82:97], v[236:239], v[224:227], v[82:97]
	v_mfma_f32_32x32x16_bf16 v[98:113], v[232:235], v[228:231], v[98:113]
	v_mfma_f32_32x32x16_bf16 v[114:129], v[236:239], v[228:231], v[114:129]
	s_waitcnt lgkmcnt(0)
	s_barrier
; DI u16 f2bf(float x) { return (u16)(pack2(x, 0.f) & 0xffffu); }
; DI float bflo(unsigned v) { return __uint_as_float(v << 16); }
; DI float bfhi(unsigned v) { return __uint_as_float(v & 0xffff0000u); }
; DI int crow(int i, int h) { return (i & 3) + 8 * (i >> 2) + 4 * h; }
; DI void phase_merge(const Params& p, int l, char* smem, int tid) {
;     ...
; #pragma unroll
;       for (int b2 = 0; b2 < 2; b2++)
; #pragma unroll
;         for (int e = 0; e < 8; e++) { accT[0][b2][2 * e] += bflo(sg[b2][e]) * t[0][b2][2 * e]; accT[0][b2][2 * e + 1] += bfhi(sg[b2][e]) * t[0][b2][2 * e + 1]; }
;     }
; #pragma unroll
;     for (int nb = 0; nb < 2; nb++) {
;       const int rowb = m0 + wm * 32, col = n0 + wn * 64 + nb * 32 + r;
; #pragma unroll
;       for (int i = 0; i < 16; i++) ACC[(size_t)(rowb + crow(i, h)) * 1024 + col] = f2bf(accT[0][nb][i]);
;     }
	v_mfma_f32_32x32x16_bf16 v[66:81], v[192:195], v[240:243], v[66:81]
	v_mfma_f32_32x32x16_bf16 v[82:97], v[196:199], v[240:243], v[82:97]
	v_mfma_f32_32x32x16_bf16 v[98:113], v[192:195], v[188:191], v[98:113]
	v_mfma_f32_32x32x16_bf16 v[114:129], v[196:199], v[188:191], v[114:129]
	s_nop 7
	s_nop 7
	v_lshlrev_b32_e32 v147, 16, v156
	v_and_b32_e32 v149, 0xffff0000, v156
	v_fmac_f32_e32 v2, v147, v66
	v_fmac_f32_e32 v3, v149, v67
	v_lshlrev_b32_e32 v151, 16, v157
	v_and_b32_e32 v153, 0xffff0000, v157
	v_fmac_f32_e32 v4, v151, v68
	v_fmac_f32_e32 v5, v153, v69
	v_lshlrev_b32_e32 v147, 16, v158
	v_and_b32_e32 v149, 0xffff0000, v158
	v_fmac_f32_e32 v6, v147, v70
	v_fmac_f32_e32 v7, v149, v71
	v_lshlrev_b32_e32 v151, 16, v159
	v_and_b32_e32 v153, 0xffff0000, v159
	v_fmac_f32_e32 v8, v151, v72
	v_fmac_f32_e32 v9, v153, v73
	v_lshlrev_b32_e32 v147, 16, v160
	v_and_b32_e32 v149, 0xffff0000, v160
	v_fmac_f32_e32 v10, v147, v74
	v_fmac_f32_e32 v11, v149, v75
	v_lshlrev_b32_e32 v151, 16, v161
	v_and_b32_e32 v153, 0xffff0000, v161
	v_fmac_f32_e32 v12, v151, v76
	v_fmac_f32_e32 v13, v153, v77
	v_lshlrev_b32_e32 v147, 16, v162
	v_and_b32_e32 v149, 0xffff0000, v162
	v_fmac_f32_e32 v14, v147, v78
	v_fmac_f32_e32 v15, v149, v79
	v_lshlrev_b32_e32 v151, 16, v163
	v_and_b32_e32 v153, 0xffff0000, v163
	v_fmac_f32_e32 v16, v151, v80
	v_fmac_f32_e32 v17, v153, v81
	v_lshlrev_b32_e32 v147, 16, v164
	v_and_b32_e32 v149, 0xffff0000, v164
	v_fmac_f32_e32 v18, v147, v82
	v_fmac_f32_e32 v19, v149, v83
	v_lshlrev_b32_e32 v151, 16, v165
	v_and_b32_e32 v153, 0xffff0000, v165
	v_fmac_f32_e32 v20, v151, v84
	v_fmac_f32_e32 v21, v153, v85
	v_lshlrev_b32_e32 v147, 16, v166
	v_and_b32_e32 v149, 0xffff0000, v166
	v_fmac_f32_e32 v22, v147, v86
	v_fmac_f32_e32 v23, v149, v87
	v_lshlrev_b32_e32 v151, 16, v167
	v_and_b32_e32 v153, 0xffff0000, v167
	v_fmac_f32_e32 v24, v151, v88
	v_fmac_f32_e32 v25, v153, v89
	v_lshlrev_b32_e32 v147, 16, v168
	v_and_b32_e32 v149, 0xffff0000, v168
	v_fmac_f32_e32 v26, v147, v90
	v_fmac_f32_e32 v27, v149, v91
	v_lshlrev_b32_e32 v151, 16, v169
	v_and_b32_e32 v153, 0xffff0000, v169
	v_fmac_f32_e32 v28, v151, v92
	v_fmac_f32_e32 v29, v153, v93
	v_lshlrev_b32_e32 v147, 16, v170
	v_and_b32_e32 v149, 0xffff0000, v170
	v_fmac_f32_e32 v30, v147, v94
	v_fmac_f32_e32 v31, v149, v95
	v_lshlrev_b32_e32 v151, 16, v171
	v_and_b32_e32 v153, 0xffff0000, v171
	v_fmac_f32_e32 v32, v151, v96
	v_fmac_f32_e32 v33, v153, v97
	v_lshlrev_b32_e32 v147, 16, v172
	v_and_b32_e32 v149, 0xffff0000, v172
	v_fmac_f32_e32 v34, v147, v98
	v_fmac_f32_e32 v35, v149, v99
	v_lshlrev_b32_e32 v151, 16, v173
	v_and_b32_e32 v153, 0xffff0000, v173
	v_fmac_f32_e32 v36, v151, v100
	v_fmac_f32_e32 v37, v153, v101
	v_lshlrev_b32_e32 v147, 16, v174
	v_and_b32_e32 v149, 0xffff0000, v174
	v_fmac_f32_e32 v38, v147, v102
	v_fmac_f32_e32 v39, v149, v103
	v_lshlrev_b32_e32 v151, 16, v175
	v_and_b32_e32 v153, 0xffff0000, v175
	v_fmac_f32_e32 v40, v151, v104
	v_fmac_f32_e32 v41, v153, v105
	v_lshlrev_b32_e32 v147, 16, v176
	v_and_b32_e32 v149, 0xffff0000, v176
	v_fmac_f32_e32 v42, v147, v106
	v_fmac_f32_e32 v43, v149, v107
	v_lshlrev_b32_e32 v151, 16, v177
	v_and_b32_e32 v153, 0xffff0000, v177
	v_fmac_f32_e32 v44, v151, v108
	v_fmac_f32_e32 v45, v153, v109
	v_lshlrev_b32_e32 v147, 16, v178
	v_and_b32_e32 v149, 0xffff0000, v178
	v_fmac_f32_e32 v46, v147, v110
	v_fmac_f32_e32 v47, v149, v111
	v_lshlrev_b32_e32 v151, 16, v179
	v_and_b32_e32 v153, 0xffff0000, v179
	v_fmac_f32_e32 v48, v151, v112
	v_fmac_f32_e32 v49, v153, v113
	v_lshlrev_b32_e32 v147, 16, v180
	v_and_b32_e32 v149, 0xffff0000, v180
	v_fmac_f32_e32 v50, v147, v114
	v_fmac_f32_e32 v51, v149, v115
	v_lshlrev_b32_e32 v151, 16, v181
	v_and_b32_e32 v153, 0xffff0000, v181
	v_fmac_f32_e32 v52, v151, v116
	v_fmac_f32_e32 v53, v153, v117
	v_lshlrev_b32_e32 v147, 16, v182
	v_and_b32_e32 v149, 0xffff0000, v182
	v_fmac_f32_e32 v54, v147, v118
	v_fmac_f32_e32 v55, v149, v119
	v_lshlrev_b32_e32 v151, 16, v183
	v_and_b32_e32 v153, 0xffff0000, v183
	v_fmac_f32_e32 v56, v151, v120
	v_fmac_f32_e32 v57, v153, v121
	v_lshlrev_b32_e32 v147, 16, v184
	v_and_b32_e32 v149, 0xffff0000, v184
	v_fmac_f32_e32 v58, v147, v122
	v_fmac_f32_e32 v59, v149, v123
	v_lshlrev_b32_e32 v151, 16, v185
	v_and_b32_e32 v153, 0xffff0000, v185
	v_fmac_f32_e32 v60, v151, v124
	v_fmac_f32_e32 v61, v153, v125
	v_lshlrev_b32_e32 v147, 16, v186
	v_and_b32_e32 v149, 0xffff0000, v186
	v_fmac_f32_e32 v62, v147, v126
	v_fmac_f32_e32 v63, v149, v127
	v_lshlrev_b32_e32 v151, 16, v187
	v_and_b32_e32 v153, 0xffff0000, v187
	v_fmac_f32_e32 v64, v151, v128
	v_fmac_f32_e32 v65, v153, v129
	s_add_u32 s13, s13, 1
	s_cmp_lt_u32 s13, 8
	s_cbranch_scc1 .Lmg_seg
	s_sub_u32 s6, s2, s96
	s_subb_u32 s7, s3, s97
	s_add_u32 s6, s6, s90
	s_addc_u32 s7, s7, s91
	s_lshr_b32 s8, s19, 10
	s_add_u32 s6, s6, s8
	s_addc_u32 s7, s7, 0
	s_add_u32 s8, s6, 0x10000
	s_addc_u32 s9, s7, 0
	v_cvt_pk_bf16_f32 v224, v2, v3
	v_cvt_pk_bf16_f32 v225, v4, v5
	global_store_dwordx2 v146, v[224:225], s[6:7] offset:0
	v_cvt_pk_bf16_f32 v226, v6, v7
	v_cvt_pk_bf16_f32 v227, v8, v9
	global_store_dwordx2 v146, v[226:227], s[6:7] offset:16
	v_cvt_pk_bf16_f32 v228, v10, v11
	v_cvt_pk_bf16_f32 v229, v12, v13
	global_store_dwordx2 v146, v[228:229], s[6:7] offset:32
	v_cvt_pk_bf16_f32 v230, v14, v15
	v_cvt_pk_bf16_f32 v231, v16, v17
	global_store_dwordx2 v146, v[230:231], s[6:7] offset:48
	v_cvt_pk_bf16_f32 v224, v18, v19
	v_cvt_pk_bf16_f32 v225, v20, v21
	global_store_dwordx2 v146, v[224:225], s[6:7] offset:64
	v_cvt_pk_bf16_f32 v226, v22, v23
	v_cvt_pk_bf16_f32 v227, v24, v25
	global_store_dwordx2 v146, v[226:227], s[6:7] offset:80
	v_cvt_pk_bf16_f32 v228, v26, v27
	v_cvt_pk_bf16_f32 v229, v28, v29
	global_store_dwordx2 v146, v[228:229], s[6:7] offset:96
	v_cvt_pk_bf16_f32 v230, v30, v31
	v_cvt_pk_bf16_f32 v231, v32, v33
	global_store_dwordx2 v146, v[230:231], s[6:7] offset:112
	v_cvt_pk_bf16_f32 v224, v34, v35
	v_cvt_pk_bf16_f32 v225, v36, v37
	global_store_dwordx2 v146, v[224:225], s[8:9] offset:0
	v_cvt_pk_bf16_f32 v226, v38, v39
	v_cvt_pk_bf16_f32 v227, v40, v41
	global_store_dwordx2 v146, v[226:227], s[8:9] offset:16
	v_cvt_pk_bf16_f32 v228, v42, v43
	v_cvt_pk_bf16_f32 v229, v44, v45
	global_store_dwordx2 v146, v[228:229], s[8:9] offset:32
	v_cvt_pk_bf16_f32 v230, v46, v47
	v_cvt_pk_bf16_f32 v231, v48, v49
	global_store_dwordx2 v146, v[230:231], s[8:9] offset:48
	v_cvt_pk_bf16_f32 v224, v50, v51
	v_cvt_pk_bf16_f32 v225, v52, v53
	global_store_dwordx2 v146, v[224:225], s[8:9] offset:64
	v_cvt_pk_bf16_f32 v226, v54, v55
	v_cvt_pk_bf16_f32 v227, v56, v57
	global_store_dwordx2 v146, v[226:227], s[8:9] offset:80
	v_cvt_pk_bf16_f32 v228, v58, v59
	v_cvt_pk_bf16_f32 v229, v60, v61
	global_store_dwordx2 v146, v[228:229], s[8:9] offset:96
	v_cvt_pk_bf16_f32 v230, v62, v63
	v_cvt_pk_bf16_f32 v231, v64, v65
	global_store_dwordx2 v146, v[230:231], s[8:9] offset:112
	s_cmp_eq_u32 s18, 0
	s_cbranch_scc1 .Lmg_item
	s_add_u32 s12, s12, s49
	s_branch .Lmg_item

; DI int fetch_item(unsigned* ctr, char* smem) {
;   volatile int* slot = (volatile int*)(smem + SMEM_BYTES - 16);
;   __syncthreads();
;   if (threadIdx.x == 0) *slot = (int)__hip_atomic_fetch_add(ctr, 1u, __ATOMIC_RELAXED, __HIP_MEMORY_SCOPE_AGENT);
;   __syncthreads();
;   return *slot;
; }
; DI void phase_outproj(const Params& p, int l, char* smem, int tid) {
;   const int lane = tid & 63, w = tid >> 6, r = lane & 31, h = lane >> 5, wm = w >> 1, wn = w & 1;
;   GemmLds* s = (GemmLds*)smem;
;   const u16* ACC = p.Pk;
;   const bool dyn = (l == 0);
;   unsigned* qc = p.bar + 4096 + 384;
;   for (int it = (dyn ? fetch_item(qc, smem) : (int)blockIdx.x); it < 272 * 8; it = (dyn ? fetch_item(qc, smem) : it + (int)gridDim.x)) {
;     const int mt = it >> 3, nt = it & 7, m0 = mt * 128, n0 = nt * 128;
;     if (l == 1 && (mt % 34) < 2) continue;
;     f32x16 acc[2][2]; zero_acc<2>(acc);
;     gemm_main<2>(ACC + (size_t)m0 * 1024, 1024, p.WtOut + (size_t)l * 1024 * 1024 + (size_t)n0 * 1024, 1024, 1024, acc, s, tid);
;     u16* O = p.G;
.LBB0_1221:
	s_or_b64 exec, exec, s[4:5]
	v_mov_b32_e32 v0, v206
	s_and_b64 vcc, exec, s[0:1]
	v_mov_b32_e32 v146, s48
	s_waitcnt lgkmcnt(0)
	s_barrier
	v_readlane_b32 s18, v254, 19
	v_and_b32_e32 v112, 63, v206
	v_lshrrev_b32_e32 v113, 6, v206
	v_lshrrev_b32_e32 v114, 3, v112
	v_lshl_add_u32 v114, v113, 5, v114
	v_lshlrev_b32_e32 v114, 11, v114
	v_and_b32_e32 v115, 7, v112
	v_lshrrev_b32_e32 v112, 4, v112
	v_xor_b32_e32 v115, v115, v112
	v_lshl_or_b32 v98, v115, 4, v114
	v_xor_b32_e32 v99, 64, v98
	v_add_u32_e32 v99, 16384, v99
	v_add_u32_e32 v100, 32768, v98
	v_add_u32_e32 v101, 32768, v99
	v_lshrrev_b32_e32 v156, 6, v206
	v_and_b32_e32 v112, 31, v206
	v_bfe_u32 v113, v206, 5, 1
	v_bfe_u32 v114, v112, 1, 3
	v_xor_b32_e32 v114, v114, v113
	v_lshlrev_b32_e32 v114, 4, v114
	v_lshl_or_b32 v114, v112, 7, v114
	v_lshrrev_b32_e32 v115, 7, v206
	v_lshl_add_u32 v102, v115, 13, v114
	v_bfe_u32 v115, v206, 6, 1
	v_lshl_add_u32 v106, v115, 13, v114
	v_add_u32_e32 v106, 0x4000, v106
	v_xor_b32_e32 v103, 32, v102
	v_xor_b32_e32 v107, 32, v106
	v_xor_b32_e32 v104, 64, v102
	v_xor_b32_e32 v108, 64, v106
	v_xor_b32_e32 v105, 96, v102
	v_xor_b32_e32 v109, 96, v106
	v_and_b32_e32 v112, 31, v206
	v_lshrrev_b32_e32 v113, 7, v206
	v_lshl_add_u32 v112, v113, 6, v112
	v_lshlrev_b32_e32 v112, 11, v112
	v_bfe_u32 v113, v206, 6, 1
	v_bfe_u32 v114, v206, 5, 1
	v_lshlrev_b32_e32 v115, 7, v113
	v_lshl_or_b32 v115, v114, 3, v115
	v_or_b32_e32 v110, v112, v115
	v_lshlrev_b32_e32 v111, 8, v113
	v_lshl_or_b32 v111, v114, 4, v111
	v_readfirstlane_b32 s10, v156
	s_lshl_b32 s10, s10, 12
	s_lshl_b32 s6, s18, 21
	s_add_u32 s14, s96, 0x1cc00000
	s_addc_u32 s15, s97, 0
	s_add_u32 s14, s14, s6
	s_addc_u32 s15, s15, 0
	s_mov_b32 s12, s48
.Lop_item:
	s_cmp_eq_u32 s18, 0
	s_cbranch_scc0 .Lop_static
	s_barrier
	s_cmp_eq_u32 s10, 0
	s_cbranch_scc0 .Lop_fetch_wait
	s_mov_b64 s[6:7], exec
	s_mov_b64 exec, 1
	s_add_u32 s8, s96, 0x1da5d600
	s_addc_u32 s9, s97, 0
	v_mov_b32_e32 v112, 1
	v_mov_b32_e32 v113, 0
	global_atomic_add v114, v113, v112, s[8:9] sc0
	v_mov_b32_e32 v115, 0x125f0
	s_waitcnt vmcnt(0)
	ds_write_b32 v115, v114
	s_waitcnt lgkmcnt(0)
	s_mov_b64 exec, s[6:7]
.Lop_fetch_wait:
	s_barrier
	v_mov_b32_e32 v115, 0x125f0
	ds_read_b32 v114, v115
	s_waitcnt lgkmcnt(0)
	v_readfirstlane_b32 s12, v114
	s_cmpk_lt_u32 s12, 0x880
	s_cbranch_scc0 .Lop_done
	s_lshr_b32 s20, s12, 3
	s_mul_hi_u32 s6, s20, 0x78787879
	s_lshr_b32 s6, s6, 4
	s_mul_i32 s7, s6, 34
	s_sub_u32 s7, s20, s7
	s_cmp_lt_u32 s7, 2
	s_cselect_b32 s6, 8, s6
	s_branch .Lop_decoded
.Lop_static:
	s_cmpk_lt_u32 s12, 0x800
	s_cbranch_scc0 .Lop_done
	s_lshr_b32 s6, s12, 8
	s_mul_i32 s7, s6, 34
	s_bfe_u32 s20, s12, 0x50003
	s_add_u32 s20, s20, s7
	s_add_u32 s20, s20, 2
.Lop_decoded:
	s_and_b32 s13, s12, 7
	s_mul_i32 s7, s18, 9
	s_add_u32 s7, s7, s6
	s_mul_i32 s7, s7, 0x3000
	s_lshl_b32 s6, s13, 9
	s_add_u32 s7, s7, s6
	s_add_u32 s7, s7, 0x1d002000
	s_add_u32 s6, s96, s7
	s_addc_u32 s7, s97, 0
	global_load_dwordx4 v[116:119], v111, s[6:7] offset:0
	global_load_dwordx4 v[120:123], v111, s[6:7] offset:32
	global_load_dwordx4 v[124:127], v111, s[6:7] offset:64
	global_load_dwordx4 v[128:131], v111, s[6:7] offset:96
	global_load_dwordx4 v[132:135], v111, s[6:7] offset:128
	global_load_dwordx4 v[136:139], v111, s[6:7] offset:160
	global_load_dwordx4 v[140:143], v111, s[6:7] offset:192
	global_load_dwordx4 v[144:147], v111, s[6:7] offset:224
	s_lshl_b32 s2, s20, 18
	s_add_u32 s4, s90, s2
	s_addc_u32 s5, s91, 0
	s_lshl_b32 s3, s13, 18
	s_add_u32 s8, s14, s3
	s_addc_u32 s9, s15, 0
	s_lshl_b32 s3, s13, 8
	s_add_u32 s2, s2, s3
	s_add_u32 s2, s2, 0x16720000
	s_add_u32 s16, s96, s2
	s_addc_u32 s17, s97, 0
	s_add_u32 s20, s16, 0x10000
	s_addc_u32 s21, s17, 0
	v_mov_b32_e32 v2, 0
	v_mov_b32_e32 v3, 0
	v_mov_b32_e32 v4, 0
	v_mov_b32_e32 v5, 0
	v_mov_b32_e32 v6, 0
	v_mov_b32_e32 v7, 0
	v_mov_b32_e32 v8, 0
	v_mov_b32_e32 v9, 0
	v_mov_b32_e32 v10, 0
	v_mov_b32_e32 v11, 0
	v_mov_b32_e32 v12, 0
	v_mov_b32_e32 v13, 0
	v_mov_b32_e32 v14, 0
	v_mov_b32_e32 v15, 0
	v_mov_b32_e32 v16, 0
	v_mov_b32_e32 v17, 0
	v_mov_b32_e32 v18, 0
	v_mov_b32_e32 v19, 0
	v_mov_b32_e32 v20, 0
	v_mov_b32_e32 v21, 0
	v_mov_b32_e32 v22, 0
	v_mov_b32_e32 v23, 0
	v_mov_b32_e32 v24, 0
	v_mov_b32_e32 v25, 0
	v_mov_b32_e32 v26, 0
	v_mov_b32_e32 v27, 0
	v_mov_b32_e32 v28, 0
	v_mov_b32_e32 v29, 0
	v_mov_b32_e32 v30, 0
	v_mov_b32_e32 v31, 0
	v_mov_b32_e32 v32, 0
	v_mov_b32_e32 v33, 0
	v_mov_b32_e32 v34, 0
	v_mov_b32_e32 v35, 0
	v_mov_b32_e32 v36, 0
	v_mov_b32_e32 v37, 0
	v_mov_b32_e32 v38, 0
	v_mov_b32_e32 v39, 0
	v_mov_b32_e32 v40, 0
	v_mov_b32_e32 v41, 0
	v_mov_b32_e32 v42, 0
	v_mov_b32_e32 v43, 0
	v_mov_b32_e32 v44, 0
	v_mov_b32_e32 v45, 0
	v_mov_b32_e32 v46, 0
	v_mov_b32_e32 v47, 0
	v_mov_b32_e32 v48, 0
	v_mov_b32_e32 v49, 0
	v_mov_b32_e32 v50, 0
	v_mov_b32_e32 v51, 0
	v_mov_b32_e32 v52, 0
	v_mov_b32_e32 v53, 0
	v_mov_b32_e32 v54, 0
	v_mov_b32_e32 v55, 0
	v_mov_b32_e32 v56, 0
	v_mov_b32_e32 v57, 0
	v_mov_b32_e32 v58, 0
	v_mov_b32_e32 v59, 0
	v_mov_b32_e32 v60, 0
	v_mov_b32_e32 v61, 0
	v_mov_b32_e32 v62, 0
	v_mov_b32_e32 v63, 0
	v_mov_b32_e32 v64, 0
	v_mov_b32_e32 v65, 0
	s_add_u32 m0, s10, 0x0
	s_nop 0
	global_load_lds_dwordx4 v98, s[4:5]
	s_add_u32 m0, s10, 0x400
	s_nop 0
	global_load_lds_dwordx4 v99, s[4:5]
	s_add_u32 m0, s10, 0x800
	s_nop 0
	global_load_lds_dwordx4 v100, s[4:5]
	s_add_u32 m0, s10, 0xc00
	s_nop 0
	global_load_lds_dwordx4 v101, s[4:5]
	s_add_u32 m0, s10, 0x4000
	s_nop 0
	global_load_lds_dwordx4 v98, s[8:9]
	s_add_u32 m0, s10, 0x4400
	s_nop 0
	global_load_lds_dwordx4 v99, s[8:9]
	s_add_u32 m0, s10, 0x4800
	s_nop 0
	global_load_lds_dwordx4 v100, s[8:9]
	s_add_u32 m0, s10, 0x4c00
	s_nop 0
	global_load_lds_dwordx4 v101, s[8:9]
	s_add_u32 s4, s4, 128
	s_addc_u32 s5, s5, 0
	s_add_u32 s8, s8, 128
	s_addc_u32 s9, s9, 0
	s_waitcnt vmcnt(0) lgkmcnt(0)
	s_barrier
	ds_read_b128 v[66:69], v102 offset:0
	ds_read_b128 v[74:77], v106 offset:0
	ds_read_b128 v[70:73], v102 offset:4096
	ds_read_b128 v[78:81], v106 offset:4096
	s_mov_b32 s11, 7
; #define G_STORE(S, bf) { *(uint4*)&s->a[bf][srow][skc] = S##a0; *(uint4*)&s->a[bf][srow + 32][skc] = S##a1; \
;     if (MB == 2) { *(uint4*)&s->a[bf][srow + 64][skc] = S##a2; *(uint4*)&s->a[bf][srow + 96][skc] = S##a3; } \
;     *(uint4*)&s->b[bf][srow][skc] = S##b0; *(uint4*)&s->b[bf][srow + 32][skc] = S##b1; *(uint4*)&s->b[bf][srow + 64][skc] = S##b2; *(uint4*)&s->b[bf][srow + 96][skc] = S##b3; }
; template <int MB, bool PF2 = true>
; DI void gemm_main(const u16* __restrict__ A, int lda, const u16* __restrict__ B, int ldb, int K, f32x16 (&acc)[MB][2], GemmLds* s, int tid) {
;     ...
;   for (int kt = 0; kt < KT; kt += 2) {
;     { const int k2 = min((kt + 2) * 64, klast); G_LOAD(q, k2); }
;     __builtin_amdgcn_sched_barrier(0);
;     G_COMPUTE(0);
;     G_STORE(p, 1);
;     __syncthreads();
;     { const int k3 = min((kt + 3) * 64, klast); G_LOAD(p, k3); }
;     __builtin_amdgcn_sched_barrier(0);
;     G_COMPUTE(1);
;     G_STORE(q, 0);
;     __syncthreads();
;   }
.Lop_loop:
	s_add_u32 m0, s10, 0x8000
	ds_read_b128 v[82:85], v103 offset:0
	global_load_lds_dwordx4 v98, s[4:5]
	s_add_u32 m0, s10, 0x8400
	ds_read_b128 v[90:93], v107 offset:0
	global_load_lds_dwordx4 v99, s[4:5]
	s_add_u32 m0, s10, 0x8800
	ds_read_b128 v[86:89], v103 offset:4096
	global_load_lds_dwordx4 v100, s[4:5]
	s_add_u32 m0, s10, 0x8c00
	ds_read_b128 v[94:97], v107 offset:4096
	global_load_lds_dwordx4 v101, s[4:5]
	s_add_u32 m0, s10, 0xc000
	s_add_u32 s4, s4, 128
	s_addc_u32 s5, s5, 0
	global_load_lds_dwordx4 v98, s[8:9]
	s_add_u32 m0, s10, 0xc400
	s_nop 0
	global_load_lds_dwordx4 v99, s[8:9]
	s_add_u32 m0, s10, 0xc800
	s_nop 0
	global_load_lds_dwordx4 v100, s[8:9]
	s_add_u32 m0, s10, 0xcc00
	s_nop 0
	global_load_lds_dwordx4 v101, s[8:9]
	s_add_u32 s8, s8, 128
	s_addc_u32 s9, s9, 0
	s_waitcnt lgkmcnt(4)
	v_mfma_f32_32x32x16_bf16 v[2:17], v[74:77], v[66:69], v[2:17]
	v_mfma_f32_32x32x16_bf16 v[18:33], v[78:81], v[66:69], v[18:33]
	v_mfma_f32_32x32x16_bf16 v[34:49], v[74:77], v[70:73], v[34:49]
	v_mfma_f32_32x32x16_bf16 v[50:65], v[78:81], v[70:73], v[50:65]
	ds_read_b128 v[66:69], v104 offset:0
	ds_read_b128 v[74:77], v108 offset:0
	ds_read_b128 v[70:73], v104 offset:4096
	ds_read_b128 v[78:81], v108 offset:4096
	s_waitcnt lgkmcnt(4)
	v_mfma_f32_32x32x16_bf16 v[2:17], v[90:93], v[82:85], v[2:17]
	v_mfma_f32_32x32x16_bf16 v[18:33], v[94:97], v[82:85], v[18:33]
	v_mfma_f32_32x32x16_bf16 v[34:49], v[90:93], v[86:89], v[34:49]
	v_mfma_f32_32x32x16_bf16 v[50:65], v[94:97], v[86:89], v[50:65]
	ds_read_b128 v[82:85], v105 offset:0
	ds_read_b128 v[90:93], v109 offset:0
	ds_read_b128 v[86:89], v105 offset:4096
	ds_read_b128 v[94:97], v109 offset:4096
	s_waitcnt lgkmcnt(4)
	v_mfma_f32_32x32x16_bf16 v[2:17], v[74:77], v[66:69], v[2:17]
	v_mfma_f32_32x32x16_bf16 v[18:33], v[78:81], v[66:69], v[18:33]
	v_mfma_f32_32x32x16_bf16 v[34:49], v[74:77], v[70:73], v[34:49]
	v_mfma_f32_32x32x16_bf16 v[50:65], v[78:81], v[70:73], v[50:65]
	s_waitcnt vmcnt(0) lgkmcnt(0)
	s_barrier
	ds_read_b128 v[66:69], v102 offset:32768
	ds_read_b128 v[74:77], v106 offset:32768
	ds_read_b128 v[70:73], v102 offset:36864
	ds_read_b128 v[78:81], v106 offset:36864
	v_mfma_f32_32x32x16_bf16 v[2:17], v[90:93], v[82:85], v[2:17]
	v_mfma_f32_32x32x16_bf16 v[18:33], v[94:97], v[82:85], v[18:33]
	v_mfma_f32_32x32x16_bf16 v[34:49], v[90:93], v[86:89], v[34:49]
	v_mfma_f32_32x32x16_bf16 v[50:65], v[94:97], v[86:89], v[50:65]
	s_cmp_eq_u32 s11, 0
	s_cbranch_scc1 .Lop_last
	s_add_u32 m0, s10, 0x0
	ds_read_b128 v[82:85], v103 offset:32768
	global_load_lds_dwordx4 v98, s[4:5]
	s_add_u32 m0, s10, 0x400
	ds_read_b128 v[90:93], v107 offset:32768
	global_load_lds_dwordx4 v99, s[4:5]
	s_add_u32 m0, s10, 0x800
	ds_read_b128 v[86:89], v103 offset:36864
	global_load_lds_dwordx4 v100, s[4:5]
	s_add_u32 m0, s10, 0xc00
	ds_read_b128 v[94:97], v107 offset:36864
	global_load_lds_dwordx4 v101, s[4:5]
	s_add_u32 m0, s10, 0x4000
	s_add_u32 s4, s4, 128
	s_addc_u32 s5, s5, 0
	global_load_lds_dwordx4 v98, s[8:9]
	s_add_u32 m0, s10, 0x4400
	s_nop 0
	global_load_lds_dwordx4 v99, s[8:9]
	s_add_u32 m0, s10, 0x4800
	s_nop 0
	global_load_lds_dwordx4 v100, s[8:9]
	s_add_u32 m0, s10, 0x4c00
	s_nop 0
	global_load_lds_dwordx4 v101, s[8:9]
	s_add_u32 s8, s8, 128
	s_addc_u32 s9, s9, 0
	s_waitcnt lgkmcnt(4)
	v_mfma_f32_32x32x16_bf16 v[2:17], v[74:77], v[66:69], v[2:17]
	v_mfma_f32_32x32x16_bf16 v[18:33], v[78:81], v[66:69], v[18:33]
	v_mfma_f32_32x32x16_bf16 v[34:49], v[74:77], v[70:73], v[34:49]
	v_mfma_f32_32x32x16_bf16 v[50:65], v[78:81], v[70:73], v[50:65]
	ds_read_b128 v[66:69], v104 offset:32768
	ds_read_b128 v[74:77], v108 offset:32768
	ds_read_b128 v[70:73], v104 offset:36864
	ds_read_b128 v[78:81], v108 offset:36864
	s_waitcnt lgkmcnt(4)
	v_mfma_f32_32x32x16_bf16 v[2:17], v[90:93], v[82:85], v[2:17]
	v_mfma_f32_32x32x16_bf16 v[18:33], v[94:97], v[82:85], v[18:33]
	v_mfma_f32_32x32x16_bf16 v[34:49], v[90:93], v[86:89], v[34:49]
	v_mfma_f32_32x32x16_bf16 v[50:65], v[94:97], v[86:89], v[50:65]
	ds_read_b128 v[82:85], v105 offset:32768
	ds_read_b128 v[90:93], v109 offset:32768
	ds_read_b128 v[86:89], v105 offset:36864
	ds_read_b128 v[94:97], v109 offset:36864
	s_waitcnt lgkmcnt(4)
	v_mfma_f32_32x32x16_bf16 v[2:17], v[74:77], v[66:69], v[2:17]
	v_mfma_f32_32x32x16_bf16 v[18:33], v[78:81], v[66:69], v[18:33]
	v_mfma_f32_32x32x16_bf16 v[34:49], v[74:77], v[70:73], v[34:49]
	v_mfma_f32_32x32x16_bf16 v[50:65], v[78:81], v[70:73], v[50:65]
	s_waitcnt vmcnt(0) lgkmcnt(0)
	s_barrier
	ds_read_b128 v[66:69], v102 offset:0
	ds_read_b128 v[74:77], v106 offset:0
	ds_read_b128 v[70:73], v102 offset:4096
	ds_read_b128 v[78:81], v106 offset:4096
	v_mfma_f32_32x32x16_bf16 v[2:17], v[90:93], v[82:85], v[2:17]
	v_mfma_f32_32x32x16_bf16 v[18:33], v[94:97], v[82:85], v[18:33]
	v_mfma_f32_32x32x16_bf16 v[34:49], v[90:93], v[86:89], v[34:49]
	v_mfma_f32_32x32x16_bf16 v[50:65], v[94:97], v[86:89], v[50:65]
	s_sub_u32 s11, s11, 1
	s_branch .Lop_loop
; DI u16 f2bf(float x) { return (u16)(pack2(x, 0.f) & 0xffffu); }
; DI int crow(int i, int h) { return (i & 3) + 8 * (i >> 2) + 4 * h; }
; DI void phase_outproj(const Params& p, int l, char* smem, int tid) {
;     ...
; #pragma unroll
;     for (int mb = 0; mb < 2; mb++)
; #pragma unroll
;       for (int nb = 0; nb < 2; nb++) {
;         const int rowb = m0 + wm * 64 + mb * 32, col = n0 + wn * 64 + nb * 32 + r;
;         const int b = rowb / SEQA, pos0 = rowb % SEQA;
;         const float gate = p.mod[((size_t)l * 9 + ((pos0 < CTXL) ? 8 : b)) * 3072 + 2048 + col];
; #pragma unroll
;         for (int i = 0; i < 16; i++) O[(size_t)(rowb + crow(i, h)) * 1024 + col] = f2bf(gate * acc[mb][nb][i]);
;       }
.Lop_last:
	ds_read_b128 v[82:85], v103 offset:32768
	ds_read_b128 v[90:93], v107 offset:32768
	ds_read_b128 v[86:89], v103 offset:36864
	ds_read_b128 v[94:97], v107 offset:36864
	s_waitcnt lgkmcnt(4)
	v_mfma_f32_32x32x16_bf16 v[2:17], v[74:77], v[66:69], v[2:17]
	v_mfma_f32_32x32x16_bf16 v[18:33], v[78:81], v[66:69], v[18:33]
	v_mfma_f32_32x32x16_bf16 v[34:49], v[74:77], v[70:73], v[34:49]
	v_mfma_f32_32x32x16_bf16 v[50:65], v[78:81], v[70:73], v[50:65]
	ds_read_b128 v[66:69], v104 offset:32768
	ds_read_b128 v[74:77], v108 offset:32768
	ds_read_b128 v[70:73], v104 offset:36864
	ds_read_b128 v[78:81], v108 offset:36864
	s_waitcnt lgkmcnt(4)
	v_mfma_f32_32x32x16_bf16 v[2:17], v[90:93], v[82:85], v[2:17]
	v_mfma_f32_32x32x16_bf16 v[18:33], v[94:97], v[82:85], v[18:33]
	v_mfma_f32_32x32x16_bf16 v[34:49], v[90:93], v[86:89], v[34:49]
	v_mfma_f32_32x32x16_bf16 v[50:65], v[94:97], v[86:89], v[50:65]
	ds_read_b128 v[82:85], v105 offset:32768
	ds_read_b128 v[90:93], v109 offset:32768
	ds_read_b128 v[86:89], v105 offset:36864
	ds_read_b128 v[94:97], v109 offset:36864
	s_waitcnt lgkmcnt(4)
	v_mfma_f32_32x32x16_bf16 v[2:17], v[74:77], v[66:69], v[2:17]
	v_mfma_f32_32x32x16_bf16 v[18:33], v[78:81], v[66:69], v[18:33]
	v_mfma_f32_32x32x16_bf16 v[34:49], v[74:77], v[70:73], v[34:49]
	v_mfma_f32_32x32x16_bf16 v[50:65], v[78:81], v[70:73], v[50:65]
	s_waitcnt vmcnt(0) lgkmcnt(0)
	s_barrier
	v_mfma_f32_32x32x16_bf16 v[2:17], v[90:93], v[82:85], v[2:17]
	v_mfma_f32_32x32x16_bf16 v[18:33], v[94:97], v[82:85], v[18:33]
	v_mfma_f32_32x32x16_bf16 v[34:49], v[90:93], v[86:89], v[34:49]
	v_mfma_f32_32x32x16_bf16 v[50:65], v[94:97], v[86:89], v[50:65]
	s_nop 7
	s_nop 7
	v_mul_f32_e32 v2, v116, v2
	v_mul_f32_e32 v3, v117, v3
	v_mul_f32_e32 v4, v118, v4
	v_mul_f32_e32 v5, v119, v5
	v_cvt_pk_bf16_f32 v156, v2, v3
	v_cvt_pk_bf16_f32 v157, v4, v5
	global_store_dwordx2 v110, v[156:157], s[16:17] offset:0
	v_mul_f32_e32 v6, v120, v6
	v_mul_f32_e32 v7, v121, v7
	v_mul_f32_e32 v8, v122, v8
	v_mul_f32_e32 v9, v123, v9
	v_cvt_pk_bf16_f32 v158, v6, v7
	v_cvt_pk_bf16_f32 v159, v8, v9
	global_store_dwordx2 v110, v[158:159], s[16:17] offset:16
	v_mul_f32_e32 v10, v124, v10
	v_mul_f32_e32 v11, v125, v11
	v_mul_f32_e32 v12, v126, v12
	v_mul_f32_e32 v13, v127, v13
	v_cvt_pk_bf16_f32 v160, v10, v11
	v_cvt_pk_bf16_f32 v161, v12, v13
	global_store_dwordx2 v110, v[160:161], s[16:17] offset:32
	v_mul_f32_e32 v14, v128, v14
	v_mul_f32_e32 v15, v129, v15
	v_mul_f32_e32 v16, v130, v16
	v_mul_f32_e32 v17, v131, v17
	v_cvt_pk_bf16_f32 v162, v14, v15
	v_cvt_pk_bf16_f32 v163, v16, v17
	global_store_dwordx2 v110, v[162:163], s[16:17] offset:48
	v_mul_f32_e32 v18, v132, v18
	v_mul_f32_e32 v19, v133, v19
	v_mul_f32_e32 v20, v134, v20
	v_mul_f32_e32 v21, v135, v21
	v_cvt_pk_bf16_f32 v156, v18, v19
	v_cvt_pk_bf16_f32 v157, v20, v21
	global_store_dwordx2 v110, v[156:157], s[16:17] offset:64
	v_mul_f32_e32 v22, v136, v22
	v_mul_f32_e32 v23, v137, v23
	v_mul_f32_e32 v24, v138, v24
	v_mul_f32_e32 v25, v139, v25
	v_cvt_pk_bf16_f32 v158, v22, v23
	v_cvt_pk_bf16_f32 v159, v24, v25
	global_store_dwordx2 v110, v[158:159], s[16:17] offset:80
	v_mul_f32_e32 v26, v140, v26
	v_mul_f32_e32 v27, v141, v27
	v_mul_f32_e32 v28, v142, v28
	v_mul_f32_e32 v29, v143, v29
	v_cvt_pk_bf16_f32 v160, v26, v27
	v_cvt_pk_bf16_f32 v161, v28, v29
	global_store_dwordx2 v110, v[160:161], s[16:17] offset:96
	v_mul_f32_e32 v30, v144, v30
	v_mul_f32_e32 v31, v145, v31
	v_mul_f32_e32 v32, v146, v32
	v_mul_f32_e32 v33, v147, v33
	v_cvt_pk_bf16_f32 v162, v30, v31
	v_cvt_pk_bf16_f32 v163, v32, v33
	global_store_dwordx2 v110, v[162:163], s[16:17] offset:112
	v_mul_f32_e32 v34, v116, v34
	v_mul_f32_e32 v35, v117, v35
	v_mul_f32_e32 v36, v118, v36
	v_mul_f32_e32 v37, v119, v37
	v_cvt_pk_bf16_f32 v156, v34, v35
	v_cvt_pk_bf16_f32 v157, v36, v37
	global_store_dwordx2 v110, v[156:157], s[20:21] offset:0
	v_mul_f32_e32 v38, v120, v38
	v_mul_f32_e32 v39, v121, v39
	v_mul_f32_e32 v40, v122, v40
	v_mul_f32_e32 v41, v123, v41
	v_cvt_pk_bf16_f32 v158, v38, v39
	v_cvt_pk_bf16_f32 v159, v40, v41
	global_store_dwordx2 v110, v[158:159], s[20:21] offset:16
	v_mul_f32_e32 v42, v124, v42
	v_mul_f32_e32 v43, v125, v43
	v_mul_f32_e32 v44, v126, v44
	v_mul_f32_e32 v45, v127, v45
	v_cvt_pk_bf16_f32 v160, v42, v43
	v_cvt_pk_bf16_f32 v161, v44, v45
	global_store_dwordx2 v110, v[160:161], s[20:21] offset:32
	v_mul_f32_e32 v46, v128, v46
	v_mul_f32_e32 v47, v129, v47
	v_mul_f32_e32 v48, v130, v48
	v_mul_f32_e32 v49, v131, v49
	v_cvt_pk_bf16_f32 v162, v46, v47
	v_cvt_pk_bf16_f32 v163, v48, v49
	global_store_dwordx2 v110, v[162:163], s[20:21] offset:48
	v_mul_f32_e32 v50, v132, v50
	v_mul_f32_e32 v51, v133, v51
	v_mul_f32_e32 v52, v134, v52
	v_mul_f32_e32 v53, v135, v53
	v_cvt_pk_bf16_f32 v156, v50, v51
	v_cvt_pk_bf16_f32 v157, v52, v53
	global_store_dwordx2 v110, v[156:157], s[20:21] offset:64
	v_mul_f32_e32 v54, v136, v54
	v_mul_f32_e32 v55, v137, v55
	v_mul_f32_e32 v56, v138, v56
	v_mul_f32_e32 v57, v139, v57
	v_cvt_pk_bf16_f32 v158, v54, v55
	v_cvt_pk_bf16_f32 v159, v56, v57
	global_store_dwordx2 v110, v[158:159], s[20:21] offset:80
	v_mul_f32_e32 v58, v140, v58
	v_mul_f32_e32 v59, v141, v59
	v_mul_f32_e32 v60, v142, v60
	v_mul_f32_e32 v61, v143, v61
	v_cvt_pk_bf16_f32 v160, v58, v59
	v_cvt_pk_bf16_f32 v161, v60, v61
	global_store_dwordx2 v110, v[160:161], s[20:21] offset:96
	v_mul_f32_e32 v62, v144, v62
	v_mul_f32_e32 v63, v145, v63
	v_mul_f32_e32 v64, v146, v64
	v_mul_f32_e32 v65, v147, v65
	v_cvt_pk_bf16_f32 v162, v62, v63
	v_cvt_pk_bf16_f32 v163, v64, v65
	global_store_dwordx2 v110, v[162:163], s[20:21] offset:112
	s_cmp_eq_u32 s18, 0
	s_cbranch_scc1 .Lop_item
	s_add_u32 s12, s12, s49
	s_branch .Lop_item
